# attention: tile DMA issue moved from the barrier tail into the next tile's early MFMA gaps (predicated by vcc), on top of v2
# speedup vs baseline: 1.0350x; 1.0017x over previous
; #define LAS __attribute__((address_space(3)))
; #define SBAR() __builtin_amdgcn_sched_barrier(0)
; #define VMW0() asm volatile("s_waitcnt vmcnt(0)" ::: "memory")
; template <int DQK>
; __device__ __forceinline__ void qkt(f32x16& p0, f32x16& p1, const LAS char* Ks, const bf16x8 (&qr)[DQK / 16], const int (&ka)[8], float nMB) {
;     constexpr int RB = DQK * 2, NA = (RB == 256) ? 8 : 4;
; #pragma unroll
;     for (int r = 0; r < 16; ++r) { p0[r] = nMB; p1[r] = nMB; }
; #pragma unroll
;     for (int d0 = 0; d0 < DQK / 16; ++d0) {
;         const LAS char* a = Ks + ka[d0 % NA] + (d0 / NA) * (NA * 32);
;         const bf16x8 b0 = *(const LAS bf16x8*)(a);
;         const bf16x8 b1 = *(const LAS bf16x8*)(a + 32 * RB);
;         p0 = __builtin_amdgcn_mfma_f32_32x32x16_bf16(b0, qr[d0], p0, 0, 0, 0);
;         p1 = __builtin_amdgcn_mfma_f32_32x32x16_bf16(b1, qr[d0], p1, 0, 0, 0); }
; }
; template <int DQK, bool DOUBLE> ...
;     ...
;     bf16x8 pa0, pa1, pa2, pa3;
;     __syncthreads();
;     DMA(0, 0); DMA(1, 1); VMW0(); __syncthreads();
;     if constexpr (!DOUBLE) {
;         f32x16 p0, p1;
;         DMA(2, 2);
;         int bc = 0, bn = 1, bf = 2;
;         for (int j = 0; j < NT; ++j) {
;             SBAR(); qkt<DQK>(p0, p1, K_lds + bc * K_STRIDE, qr, ka, nMB);
;             partialSM(p0, p1); finishSM(p0, p1, l_reg, pa0, pa1, pa2, pa3); SBAR();
;             pv_d0(o, vb0 + bc * V_BYTES, pa0, pa1, pa2, pa3);
;             if (j + 1 < NT) { VMW0(); __syncthreads(); if (j + 3 < NT) DMA(j + 3, bc); }
;             { const int _t = bc; bc = bn; bn = bf; bf = _t; }
.LBB0_142:
	s_mov_b32 s33, s4
	s_mov_b32 s4, s35
	s_mul_i32 s35, s5, 0x6000
	s_add_i32 s35, s35, 0
	s_lshl_b32 s41, s5, 14
	s_lshl_b32 s100, s4, 14
	s_add_i32 s100, s100, s3
	s_mul_i32 s101, s4, 0x6000
	s_add_i32 s101, s101, s2
	s_add_i32 s42, s21, 3
	s_cmp_lt_i32 s42, s71
	s_cselect_b64 vcc, -1, 0
	s_cmp_lg_u32 s21, 0
	s_cselect_b64 vcc, vcc, 0
	v_add_u32_e32 v203, s41, v191
	s_waitcnt lgkmcnt(2)
	v_mfma_f32_32x32x16_bf16 v[96:111], v[220:223], v[112:115], v[0:15]
	ds_read_b128 v[246:249], v209 offset:49152
	s_waitcnt lgkmcnt(2)
	v_mfma_f32_32x32x16_bf16 v[96:111], v[238:241], v[116:119], v[96:111]
	ds_read_b128 v[220:223], v206 offset:49280
	s_cbranch_vccz .Lattn_dma_B_1
	s_ashr_i32 s57, s56, 31
	v_lshl_add_u64 v[184:185], s[56:57], 0, v[168:169]
	v_lshlrev_b64 v[184:185], 11, v[184:185]
	v_lshl_add_u64 v[184:185], v[194:195], 0, v[184:185]
	s_mov_b32 m0, s100
	s_nop 0
	global_load_lds_dwordx4 v[184:185], off
.Lattn_dma_B_1:
	s_waitcnt lgkmcnt(2)
	v_mfma_f32_32x32x16_bf16 v[96:111], v[242:245], v[120:123], v[96:111]
	ds_read_b128 v[238:241], v207 offset:49280
	s_cbranch_vccz .Lattn_dma_B_2
	v_lshl_add_u64 v[184:185], s[56:57], 0, v[170:171]
	v_lshlrev_b64 v[184:185], 11, v[184:185]
	v_lshl_add_u64 v[184:185], v[194:195], 0, v[184:185]
	s_add_i32 m0, s100, 0x2000
	s_movk_i32 s100, 0xc00
	global_load_lds_dwordx4 v[184:185], off
.Lattn_dma_B_2:
	s_waitcnt lgkmcnt(2)
	v_mfma_f32_32x32x16_bf16 v[96:111], v[246:249], v[124:127], v[96:111]
	ds_read_b128 v[242:245], v208 offset:49280
	s_cbranch_vccz .Lattn_dma_B_3
	v_lshl_add_u64 v[184:185], s[56:57], 0, v[172:173]
	v_mad_u64_u32 v[204:205], s[42:43], v184, s100, v[196:197]
	s_add_i32 m0, s101, 0xc000
	v_mad_i32_i24 v205, v185, s100, v205
	v_lshl_add_u64 v[184:185], s[56:57], 0, v[174:175]
	global_load_lds_dwordx4 v[204:205], off
.Lattn_dma_B_3:
	s_waitcnt lgkmcnt(2)
	v_mfma_f32_32x32x16_bf16 v[96:111], v[220:223], v[128:131], v[96:111]
	ds_read_b128 v[246:249], v209 offset:49280
	s_cbranch_vccz .Lattn_dma_B_4
	v_mad_u64_u32 v[204:205], s[42:43], v184, s100, v[198:199]
	v_mad_i32_i24 v205, v185, s100, v205
	s_add_i32 m0, s101, 0xe000
	v_lshl_add_u64 v[184:185], s[56:57], 0, v[192:193]
	global_load_lds_dwordx4 v[204:205], off
.Lattn_dma_B_4:
	s_waitcnt lgkmcnt(2)
	v_mfma_f32_32x32x16_bf16 v[96:111], v[238:241], v[132:135], v[96:111]
	ds_read_b128 v[220:223], v206 offset:49408
	s_cbranch_vccz .Lattn_dma_B_5
	v_mad_u64_u32 v[204:205], s[42:43], v184, s100, v[200:201]
	v_mad_i32_i24 v205, v185, s100, v205
	s_add_i32 m0, s101, 0x10000
	s_nop 0
	global_load_lds_dwordx4 v[204:205], off
	s_add_i32 s56, s56, 64
.Lattn_dma_B_5:
	s_waitcnt lgkmcnt(2)
	v_mfma_f32_32x32x16_bf16 v[96:111], v[242:245], v[136:139], v[96:111]
	ds_read_b128 v[238:241], v207 offset:49408
	s_waitcnt lgkmcnt(2)
	v_mfma_f32_32x32x16_bf16 v[96:111], v[246:249], v[140:143], v[96:111]
	ds_read_b128 v[242:245], v208 offset:49408
	s_waitcnt lgkmcnt(2)
	v_mfma_f32_32x32x16_bf16 v[96:111], v[220:223], v[144:147], v[96:111]
	ds_read_b128 v[246:249], v209 offset:49408
	s_waitcnt lgkmcnt(2)
	v_mfma_f32_32x32x16_bf16 v[96:111], v[238:241], v[148:151], v[96:111]
	ds_read_b128 v[220:223], v206 offset:61440
	s_waitcnt lgkmcnt(2)
	v_mfma_f32_32x32x16_bf16 v[96:111], v[242:245], v[152:155], v[96:111]
	ds_read_b128 v[238:241], v207 offset:61440
	s_waitcnt lgkmcnt(2)
	v_mfma_f32_32x32x16_bf16 v[96:111], v[246:249], v[156:159], v[96:111]
	ds_read_b128 v[242:245], v208 offset:61440
	s_waitcnt lgkmcnt(2)
	v_mfma_f32_32x32x16_bf16 v[80:95], v[220:223], v[112:115], v[0:15]
	ds_read_b128 v[246:249], v209 offset:61440
	s_waitcnt lgkmcnt(2)
	v_mfma_f32_32x32x16_bf16 v[80:95], v[238:241], v[116:119], v[80:95]
	ds_read_b128 v[220:223], v206 offset:61568
	s_nop 4
	v_exp_f32_e32 v96, v96
	v_exp_f32_e32 v97, v97
	v_exp_f32_e32 v104, v104
	s_waitcnt lgkmcnt(2)
	v_mfma_f32_32x32x16_bf16 v[80:95], v[242:245], v[120:123], v[80:95]
	ds_read_b128 v[238:241], v207 offset:61568
	v_exp_f32_e32 v98, v98
	v_exp_f32_e32 v105, v105
	s_waitcnt lgkmcnt(2)
	v_mfma_f32_32x32x16_bf16 v[80:95], v[246:249], v[124:127], v[80:95]
	ds_read_b128 v[242:245], v208 offset:61568
	v_exp_f32_e32 v99, v99
	v_exp_f32_e32 v106, v106
	s_waitcnt lgkmcnt(2)
	v_mfma_f32_32x32x16_bf16 v[80:95], v[220:223], v[128:131], v[80:95]
	ds_read_b128 v[246:249], v209 offset:61568
	v_exp_f32_e32 v100, v100
	v_exp_f32_e32 v107, v107
	s_waitcnt lgkmcnt(2)
	v_mfma_f32_32x32x16_bf16 v[80:95], v[238:241], v[132:135], v[80:95]
	ds_read_b128 v[220:223], v206 offset:61696
	v_exp_f32_e32 v101, v101
	v_exp_f32_e32 v108, v108
	s_waitcnt lgkmcnt(2)
	v_mfma_f32_32x32x16_bf16 v[80:95], v[242:245], v[136:139], v[80:95]
	ds_read_b128 v[238:241], v207 offset:61696
	v_exp_f32_e32 v102, v102
	v_exp_f32_e32 v109, v109
	s_waitcnt lgkmcnt(2)
	v_mfma_f32_32x32x16_bf16 v[80:95], v[246:249], v[140:143], v[80:95]
	ds_read_b128 v[242:245], v208 offset:61696
	v_exp_f32_e32 v103, v103
	v_exp_f32_e32 v110, v110
	s_waitcnt lgkmcnt(2)
	v_mfma_f32_32x32x16_bf16 v[80:95], v[220:223], v[144:147], v[80:95]
	ds_read_b128 v[246:249], v209 offset:61696
	v_exp_f32_e32 v111, v111
	s_waitcnt lgkmcnt(2)
	v_mfma_f32_32x32x16_bf16 v[80:95], v[238:241], v[148:151], v[80:95]
	ds_read_b64_tr_b16 v[220:221], v203 offset:0
	ds_read_b64_tr_b16 v[222:223], v203 offset:2048
	v_cvt_pk_bf16_f32 v204, v96, v97
	v_cvt_pk_bf16_f32 v205, v98, v99
	v_cvt_pk_bf16_f32 v208, v104, v105
	s_waitcnt lgkmcnt(3)
; #define SBAR() __builtin_amdgcn_sched_barrier(0)
; #define PK8(P, BASE, OUT) do { u32x4 w = {cvt_pk_bf16(P[BASE + 0], P[BASE + 1]), cvt_pk_bf16(P[BASE + 2], P[BASE + 3]), cvt_pk_bf16(P[BASE + 4], P[BASE + 5]), cvt_pk_bf16(P[BASE + 6], P[BASE + 7])}; \
;     OUT = *reinterpret_cast<bf16x8*>(&w); } while (0)
; #define VMW0() asm volatile("s_waitcnt vmcnt(0)" ::: "memory")
; template <int D0> __device__ __forceinline__ void pv_one(f32x16& od, unsigned vb, bf16x8 pa0, bf16x8 pa1, bf16x8 pa2, bf16x8 pa3) {
;     const s16x4 l0 = tr_read<v_rd_off(D0, 0, 0)>(vb), h0 = tr_read<v_rd_off(D0, 0, 1)>(vb), l1 = tr_read<v_rd_off(D0, 1, 0)>(vb), h1 = tr_read<v_rd_off(D0, 1, 1)>(vb);
;     const s16x4 l2 = tr_read<v_rd_off(D0, 2, 0)>(vb), h2 = tr_read<v_rd_off(D0, 2, 1)>(vb), l3 = tr_read<v_rd_off(D0, 3, 0)>(vb), h3 = tr_read<v_rd_off(D0, 3, 1)>(vb);
;     asm volatile("s_waitcnt lgkmcnt(0)" ::: "memory"); SBAR();
;     ...
;     od = __builtin_amdgcn_mfma_f32_32x32x16_bf16(pa0, PK(l0, h0), od, 0, 0, 0);
;     od = __builtin_amdgcn_mfma_f32_32x32x16_bf16(pa1, PK(l1, h1), od, 0, 0, 0);
;     od = __builtin_amdgcn_mfma_f32_32x32x16_bf16(pa2, PK(l2, h2), od, 0, 0, 0);
;     od = __builtin_amdgcn_mfma_f32_32x32x16_bf16(pa3, PK(l3, h3), od, 0, 0, 0);
;     ...
; }
; __device__ __forceinline__ void pv_d0(f32x16 (&o)[4], unsigned vb, bf16x8 pa0, bf16x8 pa1, bf16x8 pa2, bf16x8 pa3) {
;     pv_one<0>(o[0], vb, pa0, pa1, pa2, pa3); pv_one<1>(o[1], vb, pa0, pa1, pa2, pa3); pv_one<2>(o[2], vb, pa0, pa1, pa2, pa3); pv_one<3>(o[3], vb, pa0, pa1, pa2, pa3);
; }
; __device__ __forceinline__ void partialSM(f32x16& p0, f32x16& p1) {
; #pragma unroll
;     for (int r = 0; r < 16; ++r) p0[r] = __builtin_amdgcn_exp2f(p0[r]);
; }
; __device__ __forceinline__ void finishSM(f32x16& p0, f32x16& p1, float& l_reg, bf16x8& pa0, bf16x8& pa1, bf16x8& pa2, bf16x8& pa3) {
; #pragma unroll
;     for (int r = 0; r < 16; ++r) p1[r] = __builtin_amdgcn_exp2f(p1[r]);
;     float ps = 0;
; #pragma unroll
;     for (int r = 0; r < 16; ++r) ps += p0[r];
; #pragma unroll
;     for (int r = 0; r < 16; ++r) ps += p1[r];
;     l_reg += ps;
;     ...
;     PK8(p0, 0, pa0); PK8(p0, 8, pa1); PK8(p1, 0, pa2); PK8(p1, 8, pa3);
;     ...
; }
; template <int DQK, bool DOUBLE> ...
;     ...
;             if (j + 1 < NT) { VMW0(); __syncthreads(); if (j + 3 < NT) DMA(j + 3, bc); }
;             { const int _t = bc; bc = bn; bn = bf; bf = _t; }
	v_mfma_f32_32x32x16_bf16 v[80:95], v[242:245], v[152:155], v[80:95]
	ds_read_b64_tr_b16 v[238:239], v203 offset:512
	ds_read_b64_tr_b16 v[240:241], v203 offset:2560
	v_cvt_pk_bf16_f32 v206, v100, v101
	v_cvt_pk_bf16_f32 v209, v106, v107
	s_waitcnt lgkmcnt(4)
	v_mfma_f32_32x32x16_bf16 v[80:95], v[246:249], v[156:159], v[80:95]
	ds_read_b64_tr_b16 v[242:243], v203 offset:1024
	ds_read_b64_tr_b16 v[244:245], v203 offset:3072
	v_cvt_pk_bf16_f32 v207, v102, v103
	v_cvt_pk_bf16_f32 v210, v108, v109
	v_add_f32_e32 v96, 0, v96
	v_add_f32_e32 v96, v97, v96
	s_waitcnt lgkmcnt(4)
	v_mfma_f32_32x32x16_bf16 v[16:31], v[204:207], v[220:223], v[16:31]
	ds_read_b64_tr_b16 v[246:247], v203 offset:1536
	ds_read_b64_tr_b16 v[248:249], v203 offset:3584
	v_cvt_pk_bf16_f32 v211, v110, v111
	v_add_f32_e32 v96, v98, v96
	v_add_f32_e32 v96, v99, v96
	v_add_f32_e32 v96, v100, v96
	s_waitcnt lgkmcnt(4)
	v_mfma_f32_32x32x16_bf16 v[32:47], v[204:207], v[238:241], v[32:47]
	ds_read_b64_tr_b16 v[220:221], v203 offset:4096
	ds_read_b64_tr_b16 v[222:223], v203 offset:6144
	v_exp_f32_e32 v80, v80
	v_exp_f32_e32 v81, v81
	v_exp_f32_e32 v88, v88
	v_exp_f32_e32 v89, v89
	v_add_f32_e32 v96, v101, v96
	v_add_f32_e32 v96, v102, v96
	s_waitcnt lgkmcnt(4)
	v_mfma_f32_32x32x16_bf16 v[48:63], v[204:207], v[242:245], v[48:63]
	ds_read_b64_tr_b16 v[238:239], v203 offset:4608
	ds_read_b64_tr_b16 v[240:241], v203 offset:6656
	v_exp_f32_e32 v82, v82
	v_exp_f32_e32 v83, v83
	v_exp_f32_e32 v90, v90
	v_add_f32_e32 v96, v103, v96
	v_add_f32_e32 v96, v104, v96
	s_waitcnt lgkmcnt(4)
	v_mfma_f32_32x32x16_bf16 v[64:79], v[204:207], v[246:249], v[64:79]
	ds_read_b64_tr_b16 v[242:243], v203 offset:5120
	ds_read_b64_tr_b16 v[244:245], v203 offset:7168
	v_exp_f32_e32 v84, v84
	v_exp_f32_e32 v85, v85
	v_exp_f32_e32 v91, v91
	v_add_f32_e32 v96, v105, v96
	v_add_f32_e32 v96, v106, v96
	s_waitcnt lgkmcnt(4)
	v_mfma_f32_32x32x16_bf16 v[16:31], v[208:211], v[220:223], v[16:31]
	ds_read_b64_tr_b16 v[246:247], v203 offset:5632
	ds_read_b64_tr_b16 v[248:249], v203 offset:7680
	v_exp_f32_e32 v86, v86
	v_exp_f32_e32 v87, v87
	v_exp_f32_e32 v92, v92
	v_add_f32_e32 v96, v107, v96
	v_add_f32_e32 v96, v108, v96
	s_waitcnt lgkmcnt(4)
	v_mfma_f32_32x32x16_bf16 v[32:47], v[208:211], v[238:241], v[32:47]
	ds_read_b64_tr_b16 v[220:221], v203 offset:8192
	ds_read_b64_tr_b16 v[222:223], v203 offset:10240
	v_cvt_pk_bf16_f32 v212, v80, v81
	v_cvt_pk_bf16_f32 v213, v82, v83
	v_exp_f32_e32 v93, v93
	v_add_f32_e32 v96, v109, v96
	v_add_f32_e32 v96, v110, v96
	s_waitcnt lgkmcnt(4)
	v_mfma_f32_32x32x16_bf16 v[48:63], v[208:211], v[242:245], v[48:63]
	ds_read_b64_tr_b16 v[238:239], v203 offset:8704
	ds_read_b64_tr_b16 v[240:241], v203 offset:10752
	v_cvt_pk_bf16_f32 v214, v84, v85
	v_exp_f32_e32 v94, v94
	v_add_f32_e32 v96, v111, v96
	s_waitcnt lgkmcnt(4)
	v_mfma_f32_32x32x16_bf16 v[64:79], v[208:211], v[246:249], v[64:79]
	ds_read_b64_tr_b16 v[242:243], v203 offset:9216
	ds_read_b64_tr_b16 v[244:245], v203 offset:11264
	v_cvt_pk_bf16_f32 v215, v86, v87
	v_exp_f32_e32 v95, v95
	v_add_f32_e32 v80, v80, v96
	v_add_f32_e32 v80, v81, v80
	s_waitcnt lgkmcnt(4)
	v_mfma_f32_32x32x16_bf16 v[16:31], v[212:215], v[220:223], v[16:31]
	ds_read_b64_tr_b16 v[246:247], v203 offset:9728
	ds_read_b64_tr_b16 v[248:249], v203 offset:11776
	v_cvt_pk_bf16_f32 v216, v88, v89
	v_add_f32_e32 v80, v82, v80
	v_add_f32_e32 v80, v83, v80
	v_add_f32_e32 v80, v84, v80
	s_waitcnt lgkmcnt(4)
	v_mfma_f32_32x32x16_bf16 v[32:47], v[212:215], v[238:241], v[32:47]
	ds_read_b64_tr_b16 v[220:221], v203 offset:12288
	ds_read_b64_tr_b16 v[222:223], v203 offset:14336
	v_cvt_pk_bf16_f32 v217, v90, v91
	v_add_f32_e32 v80, v85, v80
	v_add_f32_e32 v80, v86, v80
	v_add_f32_e32 v80, v87, v80
	s_waitcnt lgkmcnt(4)
	v_mfma_f32_32x32x16_bf16 v[48:63], v[212:215], v[242:245], v[48:63]
	ds_read_b64_tr_b16 v[238:239], v203 offset:12800
	ds_read_b64_tr_b16 v[240:241], v203 offset:14848
	v_cvt_pk_bf16_f32 v218, v92, v93
	s_waitcnt lgkmcnt(4)
	v_mfma_f32_32x32x16_bf16 v[64:79], v[212:215], v[246:249], v[64:79]
	ds_read_b64_tr_b16 v[242:243], v203 offset:13312
	ds_read_b64_tr_b16 v[244:245], v203 offset:15360
	v_cvt_pk_bf16_f32 v219, v94, v95
	v_add_f32_e32 v80, v88, v80
	v_add_f32_e32 v80, v89, v80
	v_add_f32_e32 v80, v90, v80
	s_waitcnt lgkmcnt(4)
	v_mfma_f32_32x32x16_bf16 v[16:31], v[216:219], v[220:223], v[16:31]
	ds_read_b64_tr_b16 v[246:247], v203 offset:13824
	ds_read_b64_tr_b16 v[248:249], v203 offset:15872
	s_mul_i32 s42, s33, 0x6000
	v_add_u32_e32 v206, s42, v161
	v_add_u32_e32 v207, s42, v165
	v_add_u32_e32 v208, s42, v167
	v_add_u32_e32 v209, s42, v187
	v_add_f32_e32 v80, v91, v80
	v_add_f32_e32 v80, v92, v80
	v_add_f32_e32 v80, v93, v80
	v_add_f32_e32 v80, v94, v80
	s_waitcnt lgkmcnt(4)
	v_mfma_f32_32x32x16_bf16 v[32:47], v[216:219], v[238:241], v[32:47]
	ds_read_b128 v[220:223], v206 offset:49152
	v_add_f32_e32 v80, v95, v80
	s_waitcnt lgkmcnt(3)
	v_mfma_f32_32x32x16_bf16 v[48:63], v[216:219], v[242:245], v[48:63]
	ds_read_b128 v[238:241], v207 offset:49152
	s_waitcnt lgkmcnt(2)
	v_mfma_f32_32x32x16_bf16 v[64:79], v[216:219], v[246:249], v[64:79]
	ds_read_b128 v[242:245], v208 offset:49152
	s_add_i32 s42, s21, 2
	s_cmp_ge_i32 s42, s71
	s_cbranch_scc1 .LBB0_145
	s_waitcnt vmcnt(0)
	s_barrier
.LBB0_145:
	s_add_i32 s21, s21, 1
	s_cmp_lg_u32 s20, s21
	v_add_f32_e32 v202, v202, v80
	s_cbranch_scc0 .LBB0_147
	s_mov_b32 s35, s5
	s_mov_b32 s5, s33
	s_branch .LBB0_142

; #define LAS __attribute__((address_space(3)))
; #define SBAR() __builtin_amdgcn_sched_barrier(0)
; #define VMW0() asm volatile("s_waitcnt vmcnt(0)" ::: "memory")
; template <int DQK>
; __device__ __forceinline__ void qkt(f32x16& p0, f32x16& p1, const LAS char* Ks, const bf16x8 (&qr)[DQK / 16], const int (&ka)[8], float nMB) {
;     constexpr int RB = DQK * 2, NA = (RB == 256) ? 8 : 4;
; #pragma unroll
;     for (int r = 0; r < 16; ++r) { p0[r] = nMB; p1[r] = nMB; }
; #pragma unroll
;     for (int d0 = 0; d0 < DQK / 16; ++d0) {
;         const LAS char* a = Ks + ka[d0 % NA] + (d0 / NA) * (NA * 32);
;         const bf16x8 b0 = *(const LAS bf16x8*)(a);
;         const bf16x8 b1 = *(const LAS bf16x8*)(a + 32 * RB);
;         p0 = __builtin_amdgcn_mfma_f32_32x32x16_bf16(b0, qr[d0], p0, 0, 0, 0);
;         p1 = __builtin_amdgcn_mfma_f32_32x32x16_bf16(b1, qr[d0], p1, 0, 0, 0); }
; }
; template <int DQK, bool DOUBLE> ...
;     ...
;     bf16x8 pa0, pa1, pa2, pa3;
;     __syncthreads();
;     DMA(0, 0); DMA(1, 1); VMW0(); __syncthreads();
;     if constexpr (!DOUBLE) {
;         f32x16 p0, p1;
;         DMA(2, 2);
;         int bc = 0, bn = 1, bf = 2;
;         for (int j = 0; j < NT; ++j) {
;             SBAR(); qkt<DQK>(p0, p1, K_lds + bc * K_STRIDE, qr, ka, nMB);
;             partialSM(p0, p1); finishSM(p0, p1, l_reg, pa0, pa1, pa2, pa3); SBAR();
;             pv_d0(o, vb0 + bc * V_BYTES, pa0, pa1, pa2, pa3);
;             if (j + 1 < NT) { VMW0(); __syncthreads(); if (j + 3 < NT) DMA(j + 3, bc); }
.LBB0_155:
	s_mov_b32 s33, s20
	s_mov_b32 s20, s35
	s_mul_i32 s35, s5, 0x6000
	s_add_i32 s35, s35, 0
	s_lshl_b32 s41, s5, 14
	s_lshl_b32 s100, s20, 14
	s_add_i32 s100, s100, s4
	s_mul_i32 s101, s20, 0x6000
	s_add_i32 s101, s101, s3
	s_add_i32 s42, s21, 3
	s_cmp_lt_i32 s42, s71
	s_cselect_b64 vcc, -1, 0
	s_cmp_lg_u32 s21, 0
	s_cselect_b64 vcc, vcc, 0
	v_add_u32_e32 v137, s41, v200
	s_waitcnt lgkmcnt(2)
	v_mfma_f32_32x32x16_bf16 v[96:111], v[222:225], v[112:115], v[0:15]
	ds_read_b128 v[246:249], v209 offset:49152
	s_waitcnt lgkmcnt(2)
	v_mfma_f32_32x32x16_bf16 v[96:111], v[238:241], v[116:119], v[96:111]
	ds_read_b128 v[222:225], v206 offset:53248
	s_cbranch_vccz .Lattn_dma_C1_1
	s_ashr_i32 s57, s56, 31
	v_lshl_add_u64 v[184:185], s[56:57], 0, v[128:129]
	v_lshlrev_b64 v[184:185], 11, v[184:185]
	v_lshl_add_u64 v[184:185], v[138:139], 0, v[184:185]
	s_mov_b32 m0, s100
	s_nop 0
	global_load_lds_dwordx4 v[184:185], off
.Lattn_dma_C1_1:
	s_waitcnt lgkmcnt(2)
	v_mfma_f32_32x32x16_bf16 v[96:111], v[242:245], v[120:123], v[96:111]
	ds_read_b128 v[238:241], v207 offset:53248
	s_cbranch_vccz .Lattn_dma_C1_2
	v_lshl_add_u64 v[184:185], s[56:57], 0, v[130:131]
	v_lshlrev_b64 v[184:185], 11, v[184:185]
	v_lshl_add_u64 v[184:185], v[138:139], 0, v[184:185]
	s_add_i32 m0, s100, 0x2000
	s_nop 0
	global_load_lds_dwordx4 v[184:185], off
.Lattn_dma_C1_2:
	s_waitcnt lgkmcnt(2)
	v_mfma_f32_32x32x16_bf16 v[96:111], v[246:249], v[124:127], v[96:111]
	ds_read_b128 v[242:245], v208 offset:53248
	s_cbranch_vccz .Lattn_dma_C1_3
	v_lshl_add_u64 v[184:185], s[56:57], 0, v[132:133]
	v_lshlrev_b64 v[184:185], 11, v[184:185]
	v_lshl_add_u64 v[184:185], v[134:135], 0, v[184:185]
	s_add_i32 m0, s101, 0xc000
	s_nop 0
	global_load_lds_dwordx4 v[184:185], off
	s_add_i32 s56, s56, 64
; template <int D0> __device__ __forceinline__ void pv_one(f32x16& od, unsigned vb, bf16x8 pa0, bf16x8 pa1, bf16x8 pa2, bf16x8 pa3) {
;     const s16x4 l0 = tr_read<v_rd_off(D0, 0, 0)>(vb), h0 = tr_read<v_rd_off(D0, 0, 1)>(vb), l1 = tr_read<v_rd_off(D0, 1, 0)>(vb), h1 = tr_read<v_rd_off(D0, 1, 1)>(vb);
;     const s16x4 l2 = tr_read<v_rd_off(D0, 2, 0)>(vb), h2 = tr_read<v_rd_off(D0, 2, 1)>(vb), l3 = tr_read<v_rd_off(D0, 3, 0)>(vb), h3 = tr_read<v_rd_off(D0, 3, 1)>(vb);
;     asm volatile("s_waitcnt lgkmcnt(0)" ::: "memory"); SBAR();
;     ...
;     od = __builtin_amdgcn_mfma_f32_32x32x16_bf16(pa0, PK(l0, h0), od, 0, 0, 0);
;     od = __builtin_amdgcn_mfma_f32_32x32x16_bf16(pa1, PK(l1, h1), od, 0, 0, 0);
;     od = __builtin_amdgcn_mfma_f32_32x32x16_bf16(pa2, PK(l2, h2), od, 0, 0, 0);
;     od = __builtin_amdgcn_mfma_f32_32x32x16_bf16(pa3, PK(l3, h3), od, 0, 0, 0);
;     ...
; }
; __device__ __forceinline__ void pv_d0(f32x16 (&o)[4], unsigned vb, bf16x8 pa0, bf16x8 pa1, bf16x8 pa2, bf16x8 pa3) {
;     pv_one<0>(o[0], vb, pa0, pa1, pa2, pa3); pv_one<1>(o[1], vb, pa0, pa1, pa2, pa3); pv_one<2>(o[2], vb, pa0, pa1, pa2, pa3); pv_one<3>(o[3], vb, pa0, pa1, pa2, pa3);
; }
; __device__ __forceinline__ void partialSM(f32x16& p0, f32x16& p1) {
; #pragma unroll
;     for (int r = 0; r < 16; ++r) p0[r] = __builtin_amdgcn_exp2f(p0[r]);
; }
; __device__ __forceinline__ void finishSM(f32x16& p0, f32x16& p1, float& l_reg, bf16x8& pa0, bf16x8& pa1, bf16x8& pa2, bf16x8& pa3) {
; #pragma unroll
;     for (int r = 0; r < 16; ++r) p1[r] = __builtin_amdgcn_exp2f(p1[r]);
;     float ps = 0;
; #pragma unroll
;     for (int r = 0; r < 16; ++r) ps += p0[r];
; #pragma unroll
;     for (int r = 0; r < 16; ++r) ps += p1[r];
;     l_reg += ps;
;     ...
;     PK8(p0, 0, pa0); PK8(p0, 8, pa1); PK8(p1, 0, pa2); PK8(p1, 8, pa3);
;     ...
; }
; template <int DQK>
; __device__ __forceinline__ void qkt(f32x16& p0, f32x16& p1, const LAS char* Ks, const bf16x8 (&qr)[DQK / 16], const int (&ka)[8], float nMB) {
;     constexpr int RB = DQK * 2, NA = (RB == 256) ? 8 : 4;
; #pragma unroll
;     for (int r = 0; r < 16; ++r) { p0[r] = nMB; p1[r] = nMB; }
; #pragma unroll
;     for (int d0 = 0; d0 < DQK / 16; ++d0) {
;         const LAS char* a = Ks + ka[d0 % NA] + (d0 / NA) * (NA * 32);
;         const bf16x8 b0 = *(const LAS bf16x8*)(a);
;         const bf16x8 b1 = *(const LAS bf16x8*)(a + 32 * RB);
.Lattn_dma_C1_3:
	s_waitcnt lgkmcnt(2)
	v_mfma_f32_32x32x16_bf16 v[80:95], v[222:225], v[112:115], v[0:15]
	ds_read_b128 v[246:249], v209 offset:53248
	s_waitcnt lgkmcnt(2)
	v_mfma_f32_32x32x16_bf16 v[80:95], v[238:241], v[116:119], v[80:95]
	ds_read_b64_tr_b16 v[222:223], v137 offset:0
	ds_read_b64_tr_b16 v[224:225], v137 offset:2048
	s_nop 3
	v_exp_f32_e32 v96, v96
	v_exp_f32_e32 v97, v97
	v_exp_f32_e32 v98, v98
	v_exp_f32_e32 v99, v99
	v_exp_f32_e32 v104, v104
	v_exp_f32_e32 v105, v105
	s_waitcnt lgkmcnt(3)
	v_mfma_f32_32x32x16_bf16 v[80:95], v[242:245], v[120:123], v[80:95]
	ds_read_b64_tr_b16 v[238:239], v137 offset:512
	ds_read_b64_tr_b16 v[240:241], v137 offset:2560
	v_exp_f32_e32 v100, v100
	v_exp_f32_e32 v101, v101
	v_exp_f32_e32 v102, v102
	v_exp_f32_e32 v103, v103
	v_exp_f32_e32 v106, v106
	v_exp_f32_e32 v107, v107
	s_waitcnt lgkmcnt(4)
	v_mfma_f32_32x32x16_bf16 v[80:95], v[246:249], v[124:127], v[80:95]
	ds_read_b64_tr_b16 v[242:243], v137 offset:1024
	ds_read_b64_tr_b16 v[244:245], v137 offset:3072
	v_cvt_pk_bf16_f32 v206, v96, v97
	v_cvt_pk_bf16_f32 v207, v98, v99
	v_cvt_pk_bf16_f32 v208, v100, v101
	v_cvt_pk_bf16_f32 v209, v102, v103
	v_exp_f32_e32 v108, v108
	v_exp_f32_e32 v109, v109
	v_add_f32_e32 v96, 0, v96
	v_add_f32_e32 v96, v97, v96
	s_waitcnt lgkmcnt(4)
	v_mfma_f32_32x32x16_bf16 v[16:31], v[206:209], v[222:225], v[16:31]
	ds_read_b64_tr_b16 v[246:247], v137 offset:1536
	ds_read_b64_tr_b16 v[248:249], v137 offset:3584
	v_exp_f32_e32 v110, v110
	v_exp_f32_e32 v111, v111
	v_add_f32_e32 v96, v98, v96
	v_add_f32_e32 v96, v99, v96
	s_waitcnt lgkmcnt(4)
	v_mfma_f32_32x32x16_bf16 v[32:47], v[206:209], v[238:241], v[32:47]
	ds_read_b64_tr_b16 v[222:223], v137 offset:4096
	ds_read_b64_tr_b16 v[224:225], v137 offset:6144
	v_cvt_pk_bf16_f32 v210, v104, v105
	v_cvt_pk_bf16_f32 v211, v106, v107
	v_exp_f32_e32 v80, v80
	v_exp_f32_e32 v81, v81
	v_exp_f32_e32 v88, v88
	v_exp_f32_e32 v89, v89
	v_add_f32_e32 v96, v100, v96
	v_add_f32_e32 v96, v101, v96
	s_waitcnt lgkmcnt(4)
	v_mfma_f32_32x32x16_bf16 v[48:63], v[206:209], v[242:245], v[48:63]
	ds_read_b64_tr_b16 v[238:239], v137 offset:4608
	ds_read_b64_tr_b16 v[240:241], v137 offset:6656
	v_cvt_pk_bf16_f32 v212, v108, v109
	v_exp_f32_e32 v82, v82
	v_exp_f32_e32 v83, v83
	v_exp_f32_e32 v90, v90
	v_add_f32_e32 v96, v102, v96
	v_add_f32_e32 v96, v103, v96
	s_waitcnt lgkmcnt(4)
	v_mfma_f32_32x32x16_bf16 v[64:79], v[206:209], v[246:249], v[64:79]
	ds_read_b64_tr_b16 v[242:243], v137 offset:5120
	ds_read_b64_tr_b16 v[244:245], v137 offset:7168
	v_cvt_pk_bf16_f32 v213, v110, v111
	v_exp_f32_e32 v84, v84
	v_exp_f32_e32 v85, v85
	v_exp_f32_e32 v91, v91
	v_add_f32_e32 v96, v104, v96
	v_add_f32_e32 v96, v105, v96
	s_waitcnt lgkmcnt(4)
	v_mfma_f32_32x32x16_bf16 v[16:31], v[210:213], v[222:225], v[16:31]
	ds_read_b64_tr_b16 v[246:247], v137 offset:5632
	ds_read_b64_tr_b16 v[248:249], v137 offset:7680
	v_exp_f32_e32 v86, v86
	v_exp_f32_e32 v87, v87
	v_exp_f32_e32 v92, v92
	v_add_f32_e32 v96, v106, v96
	v_add_f32_e32 v96, v107, v96
	s_waitcnt lgkmcnt(4)
	v_mfma_f32_32x32x16_bf16 v[32:47], v[210:213], v[238:241], v[32:47]
	ds_read_b64_tr_b16 v[222:223], v137 offset:8192
	ds_read_b64_tr_b16 v[224:225], v137 offset:10240
	v_cvt_pk_bf16_f32 v214, v80, v81
	v_cvt_pk_bf16_f32 v215, v82, v83
	v_exp_f32_e32 v93, v93
	v_add_f32_e32 v96, v108, v96
	v_add_f32_e32 v96, v109, v96
	s_waitcnt lgkmcnt(4)
	v_mfma_f32_32x32x16_bf16 v[48:63], v[210:213], v[242:245], v[48:63]
	ds_read_b64_tr_b16 v[238:239], v137 offset:8704
	ds_read_b64_tr_b16 v[240:241], v137 offset:10752
	v_cvt_pk_bf16_f32 v216, v84, v85
	v_exp_f32_e32 v94, v94
	v_add_f32_e32 v96, v110, v96
	v_add_f32_e32 v96, v111, v96
	s_waitcnt lgkmcnt(4)
	v_mfma_f32_32x32x16_bf16 v[64:79], v[210:213], v[246:249], v[64:79]
	ds_read_b64_tr_b16 v[242:243], v137 offset:9216
	ds_read_b64_tr_b16 v[244:245], v137 offset:11264
	v_cvt_pk_bf16_f32 v217, v86, v87
	v_exp_f32_e32 v95, v95
	v_add_f32_e32 v80, v80, v96
	v_add_f32_e32 v80, v81, v80
	s_waitcnt lgkmcnt(4)
	v_mfma_f32_32x32x16_bf16 v[16:31], v[214:217], v[222:225], v[16:31]
	ds_read_b64_tr_b16 v[246:247], v137 offset:9728
	ds_read_b64_tr_b16 v[248:249], v137 offset:11776
	v_cvt_pk_bf16_f32 v218, v88, v89
	v_add_f32_e32 v80, v82, v80
	v_add_f32_e32 v80, v83, v80
	v_add_f32_e32 v80, v84, v80
	s_waitcnt lgkmcnt(4)
	v_mfma_f32_32x32x16_bf16 v[32:47], v[214:217], v[238:241], v[32:47]
	ds_read_b64_tr_b16 v[222:223], v137 offset:12288
	ds_read_b64_tr_b16 v[224:225], v137 offset:14336
	v_cvt_pk_bf16_f32 v219, v90, v91
	v_add_f32_e32 v80, v85, v80
	v_add_f32_e32 v80, v86, v80
	v_add_f32_e32 v80, v87, v80
	s_waitcnt lgkmcnt(4)
	v_mfma_f32_32x32x16_bf16 v[48:63], v[214:217], v[242:245], v[48:63]
	ds_read_b64_tr_b16 v[238:239], v137 offset:12800
	ds_read_b64_tr_b16 v[240:241], v137 offset:14848
	v_cvt_pk_bf16_f32 v220, v92, v93
	s_waitcnt lgkmcnt(4)
	v_mfma_f32_32x32x16_bf16 v[64:79], v[214:217], v[246:249], v[64:79]
	ds_read_b64_tr_b16 v[242:243], v137 offset:13312
	ds_read_b64_tr_b16 v[244:245], v137 offset:15360
	v_cvt_pk_bf16_f32 v221, v94, v95
	v_add_f32_e32 v80, v88, v80
	v_add_f32_e32 v80, v89, v80
	v_add_f32_e32 v80, v90, v80
	s_waitcnt lgkmcnt(4)
	v_mfma_f32_32x32x16_bf16 v[16:31], v[218:221], v[222:225], v[16:31]
	ds_read_b64_tr_b16 v[246:247], v137 offset:13824
	ds_read_b64_tr_b16 v[248:249], v137 offset:15872
	s_mul_i32 s42, s33, 0x6000
	v_add_u32_e32 v206, s42, v145
	v_add_u32_e32 v207, s42, v161
	v_add_u32_e32 v208, s42, v198
	v_add_u32_e32 v209, s42, v199
	v_add_f32_e32 v80, v91, v80
	v_add_f32_e32 v80, v92, v80
	v_add_f32_e32 v80, v93, v80
	v_add_f32_e32 v80, v94, v80
	s_waitcnt lgkmcnt(4)
	v_mfma_f32_32x32x16_bf16 v[32:47], v[218:221], v[238:241], v[32:47]
	ds_read_b128 v[222:225], v206 offset:49152
	v_add_f32_e32 v80, v95, v80
	s_waitcnt lgkmcnt(3)
	v_mfma_f32_32x32x16_bf16 v[48:63], v[218:221], v[242:245], v[48:63]
	ds_read_b128 v[238:241], v207 offset:49152
	s_waitcnt lgkmcnt(2)
	v_mfma_f32_32x32x16_bf16 v[64:79], v[218:221], v[246:249], v[64:79]
	ds_read_b128 v[242:245], v208 offset:49152
	s_add_i32 s42, s21, 2
	s_cmp_ge_i32 s42, s71
	s_cbranch_scc1 .LBB0_158
	s_waitcnt vmcnt(0)
	s_barrier
.LBB0_158:
	s_add_i32 s21, s21, 1
	s_cmp_lg_u32 s2, s21
	v_add_f32_e32 v136, v136, v80
	s_cbranch_scc0 .LBB0_160
	s_mov_b32 s35, s5
	s_mov_b32 s5, s33
	s_branch .LBB0_155

; #define LAS __attribute__((address_space(3)))
; #define SBAR() __builtin_amdgcn_sched_barrier(0)
; #define VMW0() asm volatile("s_waitcnt vmcnt(0)" ::: "memory")
; template <int DQK>
; __device__ __forceinline__ void qkt(f32x16& p0, f32x16& p1, const LAS char* Ks, const bf16x8 (&qr)[DQK / 16], const int (&ka)[8], float nMB) {
;     constexpr int RB = DQK * 2, NA = (RB == 256) ? 8 : 4;
; #pragma unroll
;     for (int r = 0; r < 16; ++r) { p0[r] = nMB; p1[r] = nMB; }
; #pragma unroll
;     for (int d0 = 0; d0 < DQK / 16; ++d0) {
;         const LAS char* a = Ks + ka[d0 % NA] + (d0 / NA) * (NA * 32);
;         const bf16x8 b0 = *(const LAS bf16x8*)(a);
;         const bf16x8 b1 = *(const LAS bf16x8*)(a + 32 * RB);
;         p0 = __builtin_amdgcn_mfma_f32_32x32x16_bf16(b0, qr[d0], p0, 0, 0, 0);
;         p1 = __builtin_amdgcn_mfma_f32_32x32x16_bf16(b1, qr[d0], p1, 0, 0, 0); }
; }
; template <int DQK, bool DOUBLE> ...
;     ...
;     bf16x8 pa0, pa1, pa2, pa3;
;     __syncthreads();
;     DMA(0, 0); DMA(1, 1); VMW0(); __syncthreads();
;     if constexpr (!DOUBLE) {
;         f32x16 p0, p1;
;         DMA(2, 2);
;         int bc = 0, bn = 1, bf = 2;
;         for (int j = 0; j < NT; ++j) {
;             SBAR(); qkt<DQK>(p0, p1, K_lds + bc * K_STRIDE, qr, ka, nMB);
;             partialSM(p0, p1); finishSM(p0, p1, l_reg, pa0, pa1, pa2, pa3); SBAR();
;             pv_d0(o, vb0 + bc * V_BYTES, pa0, pa1, pa2, pa3);
;             if (j + 1 < NT) { VMW0(); __syncthreads(); if (j + 3 < NT) DMA(j + 3, bc); }
.LBB0_163:
	s_mov_b32 s33, s21
	s_mov_b32 s21, s35
	s_mul_i32 s35, s5, 0x6000
	s_add_i32 s35, s35, 0
	s_lshl_b32 s41, s5, 14
	s_lshl_b32 s100, s21, 14
	s_add_i32 s100, s100, s4
	s_mul_i32 s101, s21, 0x6000
	s_add_i32 s101, s101, s3
	s_add_i32 s42, s20, 3
	s_cmp_lt_i32 s42, s71
	s_cselect_b64 vcc, -1, 0
	s_cmp_lg_u32 s20, 0
	s_cselect_b64 vcc, vcc, 0
	v_add_u32_e32 v141, s41, v200
	s_waitcnt lgkmcnt(2)
	v_mfma_f32_32x32x16_bf16 v[96:111], v[202:205], v[112:115], v[48:63]
	ds_read_b128 v[214:217], v149 offset:49152
	s_waitcnt lgkmcnt(2)
	v_mfma_f32_32x32x16_bf16 v[96:111], v[206:209], v[116:119], v[96:111]
	ds_read_b128 v[202:205], v146 offset:53248
	s_cbranch_vccz .Lattn_dma_C2_1
	s_ashr_i32 s51, s50, 31
	v_lshl_add_u64 v[142:143], s[50:51], 0, v[128:129]
	v_lshlrev_b64 v[142:143], 11, v[142:143]
	v_lshl_add_u64 v[142:143], v[138:139], 0, v[142:143]
	s_mov_b32 m0, s100
	s_nop 0
	global_load_lds_dwordx4 v[142:143], off
.Lattn_dma_C2_1:
	s_waitcnt lgkmcnt(2)
	v_mfma_f32_32x32x16_bf16 v[96:111], v[210:213], v[120:123], v[96:111]
	ds_read_b128 v[206:209], v147 offset:53248
	s_cbranch_vccz .Lattn_dma_C2_2
	v_lshl_add_u64 v[142:143], s[50:51], 0, v[130:131]
	v_lshlrev_b64 v[142:143], 11, v[142:143]
	v_lshl_add_u64 v[142:143], v[138:139], 0, v[142:143]
	s_add_i32 m0, s100, 0x2000
	s_nop 0
	global_load_lds_dwordx4 v[142:143], off
.Lattn_dma_C2_2:
	s_waitcnt lgkmcnt(2)
	v_mfma_f32_32x32x16_bf16 v[96:111], v[214:217], v[124:127], v[96:111]
	ds_read_b128 v[210:213], v148 offset:53248
	s_cbranch_vccz .Lattn_dma_C2_3
	v_lshl_add_u64 v[142:143], s[50:51], 0, v[132:133]
	v_lshlrev_b64 v[142:143], 11, v[142:143]
	v_lshl_add_u64 v[142:143], v[134:135], 0, v[142:143]
	v_lshl_add_u64 v[142:143], v[142:143], 0, s[0:1]
	s_add_i32 m0, s101, 0xc000
	s_nop 0
	global_load_lds_dwordx4 v[142:143], off
	s_add_i32 s50, s50, 64
.Lattn_dma_C2_3:
	s_waitcnt lgkmcnt(2)
	v_mfma_f32_32x32x16_bf16 v[80:95], v[202:205], v[112:115], v[48:63]
	ds_read_b128 v[214:217], v149 offset:53248
	s_waitcnt lgkmcnt(2)
	v_mfma_f32_32x32x16_bf16 v[80:95], v[206:209], v[116:119], v[80:95]
	ds_read_b64_tr_b16 v[202:203], v141 offset:0
	ds_read_b64_tr_b16 v[204:205], v141 offset:2048
	s_nop 3
	v_exp_f32_e32 v96, v96
	v_exp_f32_e32 v97, v97
	v_exp_f32_e32 v98, v98
	v_exp_f32_e32 v99, v99
	v_exp_f32_e32 v104, v104
	v_exp_f32_e32 v105, v105
	s_waitcnt lgkmcnt(3)
	v_mfma_f32_32x32x16_bf16 v[80:95], v[210:213], v[120:123], v[80:95]
	ds_read_b64_tr_b16 v[206:207], v141 offset:512
	ds_read_b64_tr_b16 v[208:209], v141 offset:2560
	v_exp_f32_e32 v100, v100
	v_exp_f32_e32 v101, v101
	v_exp_f32_e32 v102, v102
	v_exp_f32_e32 v103, v103
	v_exp_f32_e32 v106, v106
	v_exp_f32_e32 v107, v107
	s_waitcnt lgkmcnt(4)
	v_mfma_f32_32x32x16_bf16 v[80:95], v[214:217], v[124:127], v[80:95]
	ds_read_b64_tr_b16 v[210:211], v141 offset:1024
	ds_read_b64_tr_b16 v[212:213], v141 offset:3072
	v_cvt_pk_bf16_f32 v146, v96, v97
	v_cvt_pk_bf16_f32 v147, v98, v99
	v_cvt_pk_bf16_f32 v148, v100, v101
	v_cvt_pk_bf16_f32 v149, v102, v103
	v_exp_f32_e32 v108, v108
	v_exp_f32_e32 v109, v109
	v_add_f32_e32 v96, 0, v96
	v_add_f32_e32 v96, v97, v96
	s_waitcnt lgkmcnt(4)
	v_mfma_f32_32x32x16_bf16 v[64:79], v[146:149], v[202:205], v[64:79]
	ds_read_b64_tr_b16 v[214:215], v141 offset:1536
	ds_read_b64_tr_b16 v[216:217], v141 offset:3584
	v_exp_f32_e32 v110, v110
	v_exp_f32_e32 v111, v111
	v_add_f32_e32 v96, v98, v96
	v_add_f32_e32 v96, v99, v96
	s_waitcnt lgkmcnt(4)
	v_mfma_f32_32x32x16_bf16 v[32:47], v[146:149], v[206:209], v[32:47]
	ds_read_b64_tr_b16 v[202:203], v141 offset:4096
	ds_read_b64_tr_b16 v[204:205], v141 offset:6144
	v_cvt_pk_bf16_f32 v150, v104, v105
	v_cvt_pk_bf16_f32 v151, v106, v107
	v_exp_f32_e32 v80, v80
	v_exp_f32_e32 v81, v81
	v_exp_f32_e32 v88, v88
	v_exp_f32_e32 v89, v89
	v_add_f32_e32 v96, v100, v96
	v_add_f32_e32 v96, v101, v96
	s_waitcnt lgkmcnt(4)
	v_mfma_f32_32x32x16_bf16 v[16:31], v[146:149], v[210:213], v[16:31]
	ds_read_b64_tr_b16 v[206:207], v141 offset:4608
	ds_read_b64_tr_b16 v[208:209], v141 offset:6656
	v_cvt_pk_bf16_f32 v152, v108, v109
	v_exp_f32_e32 v82, v82
	v_exp_f32_e32 v83, v83
	v_exp_f32_e32 v90, v90
	v_add_f32_e32 v96, v102, v96
	v_add_f32_e32 v96, v103, v96
	s_waitcnt lgkmcnt(4)
	v_mfma_f32_32x32x16_bf16 v[0:15], v[146:149], v[214:217], v[0:15]
	ds_read_b64_tr_b16 v[210:211], v141 offset:5120
	ds_read_b64_tr_b16 v[212:213], v141 offset:7168
	v_cvt_pk_bf16_f32 v153, v110, v111
	v_exp_f32_e32 v84, v84
	v_exp_f32_e32 v85, v85
	v_exp_f32_e32 v91, v91
	v_add_f32_e32 v96, v104, v96
	v_add_f32_e32 v96, v105, v96
	s_waitcnt lgkmcnt(4)
	v_mfma_f32_32x32x16_bf16 v[64:79], v[150:153], v[202:205], v[64:79]
	ds_read_b64_tr_b16 v[214:215], v141 offset:5632
	ds_read_b64_tr_b16 v[216:217], v141 offset:7680
	v_exp_f32_e32 v86, v86
	v_exp_f32_e32 v87, v87
	v_exp_f32_e32 v92, v92
	v_add_f32_e32 v96, v106, v96
	v_add_f32_e32 v96, v107, v96
	s_waitcnt lgkmcnt(4)
	v_mfma_f32_32x32x16_bf16 v[32:47], v[150:153], v[206:209], v[32:47]
	ds_read_b64_tr_b16 v[202:203], v141 offset:8192
	ds_read_b64_tr_b16 v[204:205], v141 offset:10240
	v_cvt_pk_bf16_f32 v154, v80, v81
	v_cvt_pk_bf16_f32 v155, v82, v83
	v_exp_f32_e32 v93, v93
	v_add_f32_e32 v96, v108, v96
	v_add_f32_e32 v96, v109, v96
	s_waitcnt lgkmcnt(4)
	v_mfma_f32_32x32x16_bf16 v[16:31], v[150:153], v[210:213], v[16:31]
	ds_read_b64_tr_b16 v[206:207], v141 offset:8704
	ds_read_b64_tr_b16 v[208:209], v141 offset:10752
	v_cvt_pk_bf16_f32 v156, v84, v85
	v_exp_f32_e32 v94, v94
	v_add_f32_e32 v96, v110, v96
	v_add_f32_e32 v96, v111, v96
	s_waitcnt lgkmcnt(4)
; #define LAS __attribute__((address_space(3)))
; __device__ __forceinline__ int crow(int r, int hi) { return (r & 3) + 8 * (r >> 2) + 4 * hi; }
; __device__ __forceinline__ void row_recip(float l_reg, float (&rli)[16], LAS float* li, int r32, int hi) {
;     { auto rr = __builtin_amdgcn_permlane32_swap(__float_as_uint(l_reg), __float_as_uint(l_reg), false, false);
;       l_reg = __uint_as_float(rr[0]) + __uint_as_float(rr[1]); }
;     if (hi == 0) li[r32] = l_reg;
;     asm volatile("s_waitcnt lgkmcnt(0)" ::: "memory");
; #pragma unroll
;     for (int r = 0; r < 16; ++r) rli[r] = __builtin_amdgcn_rcpf(li[crow(r, hi)]);
;     asm volatile("s_waitcnt lgkmcnt(0)" ::: "memory");
; }
; __device__ __forceinline__ void attn_item(const AttnBufs& T, int type, int b, int h, int qrow0, int NT, LAS char* lds, int tid_) {
;     ...
;         att::row_recip(l_reg, rli, li, r32, hi);
;         const float lam = T.lamv[0];
; #pragma unroll
;         for (int d0 = 0; d0 < 4; ++d0)
; #pragma unroll
;             for (int q = 0; q < 4; ++q) { const f32x4 a = scr[d0 * 4 + q];
; #pragma unroll
;                 for (int j = 0; j < 4; ++j) o[d0][q * 4 + j] = a[j] - lam * (o[d0][q * 4 + j] * rli[q * 4 + j]); }
	v_mfma_f32_32x32x16_bf16 v[0:15], v[150:153], v[214:217], v[0:15]
	ds_read_b64_tr_b16 v[210:211], v141 offset:9216
	ds_read_b64_tr_b16 v[212:213], v141 offset:11264
	v_cvt_pk_bf16_f32 v157, v86, v87
	v_exp_f32_e32 v95, v95
	v_add_f32_e32 v80, v80, v96
	v_add_f32_e32 v80, v81, v80
	s_waitcnt lgkmcnt(4)
	v_mfma_f32_32x32x16_bf16 v[64:79], v[154:157], v[202:205], v[64:79]
	ds_read_b64_tr_b16 v[214:215], v141 offset:9728
	ds_read_b64_tr_b16 v[216:217], v141 offset:11776
	v_cvt_pk_bf16_f32 v166, v88, v89
	v_add_f32_e32 v80, v82, v80
	v_add_f32_e32 v80, v83, v80
	v_add_f32_e32 v80, v84, v80
	s_waitcnt lgkmcnt(4)
	v_mfma_f32_32x32x16_bf16 v[32:47], v[154:157], v[206:209], v[32:47]
	ds_read_b64_tr_b16 v[202:203], v141 offset:12288
	ds_read_b64_tr_b16 v[204:205], v141 offset:14336
	v_cvt_pk_bf16_f32 v167, v90, v91
	v_add_f32_e32 v80, v85, v80
	v_add_f32_e32 v80, v86, v80
	v_add_f32_e32 v80, v87, v80
	s_waitcnt lgkmcnt(4)
	v_mfma_f32_32x32x16_bf16 v[16:31], v[154:157], v[210:213], v[16:31]
	ds_read_b64_tr_b16 v[206:207], v141 offset:12800
	ds_read_b64_tr_b16 v[208:209], v141 offset:14848
	v_cvt_pk_bf16_f32 v168, v92, v93
	s_waitcnt lgkmcnt(4)
	v_mfma_f32_32x32x16_bf16 v[0:15], v[154:157], v[214:217], v[0:15]
	ds_read_b64_tr_b16 v[210:211], v141 offset:13312
	ds_read_b64_tr_b16 v[212:213], v141 offset:15360
	v_cvt_pk_bf16_f32 v169, v94, v95
	v_add_f32_e32 v80, v88, v80
	v_add_f32_e32 v80, v89, v80
	v_add_f32_e32 v80, v90, v80
	s_waitcnt lgkmcnt(4)
	v_mfma_f32_32x32x16_bf16 v[64:79], v[166:169], v[202:205], v[64:79]
	ds_read_b64_tr_b16 v[214:215], v141 offset:13824
	ds_read_b64_tr_b16 v[216:217], v141 offset:15872
	s_mul_i32 s42, s33, 0x6000
	v_add_u32_e32 v146, s42, v145
	v_add_u32_e32 v147, s42, v161
	v_add_u32_e32 v148, s42, v198
	v_add_u32_e32 v149, s42, v199
	v_add_f32_e32 v80, v91, v80
	v_add_f32_e32 v80, v92, v80
	v_add_f32_e32 v80, v93, v80
	v_add_f32_e32 v80, v94, v80
	s_waitcnt lgkmcnt(4)
	v_mfma_f32_32x32x16_bf16 v[32:47], v[166:169], v[206:209], v[32:47]
	ds_read_b128 v[202:205], v146 offset:49152
	v_add_f32_e32 v80, v95, v80
	s_waitcnt lgkmcnt(3)
	v_mfma_f32_32x32x16_bf16 v[16:31], v[166:169], v[210:213], v[16:31]
	ds_read_b128 v[206:209], v147 offset:49152
	s_waitcnt lgkmcnt(2)
	v_mfma_f32_32x32x16_bf16 v[0:15], v[166:169], v[214:217], v[0:15]
	ds_read_b128 v[210:213], v148 offset:49152
	s_add_i32 s42, s20, 2
	s_cmp_ge_i32 s42, s71
	s_cbranch_scc1 .LBB0_166
	s_waitcnt vmcnt(0)
	s_barrier
.LBB0_166:
	s_add_i32 s20, s20, 1
	s_cmp_lg_u32 s2, s20
	v_add_f32_e32 v140, v140, v80
	s_cbranch_scc0 .LBB0_168
	s_mov_b32 s35, s5
	s_mov_b32 s5, s33
	s_branch .LBB0_163
.LBB0_168:
	v_cmp_gt_u32_e32 vcc, 32, v182
	s_waitcnt lgkmcnt(0)
	s_nop 11
	v_mov_b32_e32 v48, v140
	s_nop 1
	v_permlane32_swap_b32_e32 v140, v48
	s_and_saveexec_b64 s[50:51], vcc
	v_lshl_add_u32 v49, v181, 2, s90
	v_add_f32_e32 v48, v140, v48
	ds_write_b32 v49, v48
	s_or_b64 exec, exec, s[50:51]
	s_waitcnt lgkmcnt(0)
	ds_read_b128 v[48:51], v201
	ds_read_b128 v[52:55], v201 offset:32
	s_add_i32 s2, s48, 0x800
	s_movk_i32 s4, 0x1800
	s_mov_b32 s5, 0xf000
	s_waitcnt lgkmcnt(0)
	v_rcp_f32_e32 v87, v48
	v_rcp_f32_e32 v86, v49
	v_rcp_f32_e32 v85, v50
	v_rcp_f32_e32 v84, v51
	ds_read_b128 v[48:51], v201 offset:64
	v_rcp_f32_e32 v83, v52
	v_rcp_f32_e32 v82, v53
	v_rcp_f32_e32 v81, v54
	v_rcp_f32_e32 v80, v55
	s_waitcnt lgkmcnt(0)
	v_rcp_f32_e32 v91, v48
	v_rcp_f32_e32 v90, v49
	v_rcp_f32_e32 v89, v50
	v_rcp_f32_e32 v88, v51
	ds_read_b128 v[48:51], v201 offset:96
	s_waitcnt lgkmcnt(0)
	v_mul_f32_e32 v64, v64, v87
	v_mul_f32_e32 v32, v32, v87
	v_mul_f32_e32 v16, v16, v87
	s_waitcnt lgkmcnt(0)
	v_rcp_f32_e32 v95, v48
	v_rcp_f32_e32 v94, v49
	v_rcp_f32_e32 v93, v50
	v_rcp_f32_e32 v92, v51
	global_load_dword v96, v177, s[14:15]
	global_load_dwordx4 v[60:63], v[136:137], off offset:48
	global_load_dwordx4 v[56:59], v[136:137], off offset:32
	global_load_dwordx4 v[52:55], v[136:137], off offset:16
	global_load_dwordx4 v[48:51], v[136:137], off
	v_mul_f32_e32 v0, v0, v87
	s_mov_b32 s20, 0x15000
	s_mov_b32 s21, 0x1b000
	s_mov_b32 s33, 0x27000
	v_mov_b32_e32 v161, v160
	s_mov_b64 s[48:49], 0
	s_waitcnt vmcnt(0)
	v_fma_f32 v48, -v64, v96, v48
	v_mul_f32_e32 v64, v65, v86
	v_fma_f32 v49, -v64, v96, v49
	v_mul_f32_e32 v64, v66, v85
	v_fma_f32 v50, -v64, v96, v50
	v_mul_f32_e32 v64, v67, v84
	v_fma_f32 v51, -v64, v96, v51
	v_mul_f32_e32 v64, v68, v83
	v_fma_f32 v52, -v64, v96, v52
	v_mul_f32_e32 v64, v69, v82
	v_fma_f32 v53, -v64, v96, v53
	v_mul_f32_e32 v64, v70, v81
	v_fma_f32 v54, -v64, v96, v54
	v_mul_f32_e32 v64, v71, v80
	v_fma_f32 v55, -v64, v96, v55
	v_mul_f32_e32 v64, v72, v91
	v_fma_f32 v56, -v64, v96, v56
	v_mul_f32_e32 v64, v73, v90
	v_fma_f32 v57, -v64, v96, v57
	v_mul_f32_e32 v64, v74, v89
	v_fma_f32 v58, -v64, v96, v58
	v_mul_f32_e32 v64, v75, v88
	v_fma_f32 v59, -v64, v96, v59
	v_mul_f32_e32 v64, v76, v95
	v_fma_f32 v60, -v64, v96, v60
	v_mul_f32_e32 v64, v77, v94
	v_fma_f32 v61, -v64, v96, v61
	v_mul_f32_e32 v64, v78, v93
	v_fma_f32 v62, -v64, v96, v62
	v_mul_f32_e32 v64, v79, v92
	v_fma_f32 v63, -v96, v64, v63
	global_load_dwordx4 v[70:73], v[136:137], off offset:112
	global_load_dwordx4 v[74:77], v[136:137], off offset:96
	global_load_dwordx4 v[98:101], v[136:137], off offset:80
	global_load_dwordx4 v[64:67], v[136:137], off offset:64
	s_waitcnt vmcnt(0)
; #define LAS __attribute__((address_space(3)))
; template <bool SUBLN>
; __device__ __forceinline__ void attn_out(const AttnBufs& T, f32x16 (&o)[4], int type, int h, size_t orow0, LAS char* lds, int wid, int lane, int r32, int hi) {
;     const int rr = lane >> 5, c4 = (lane & 31) * 4;
;     const int col = type * 1024 + h * 128 + c4;
;     const bf16_t* gp = T.GATE + (orow0 + rr) * 3072 + col; bf16_t* op = T.BR + (orow0 + rr) * 3072 + col;
;     u32x2 gg[16];
; #pragma unroll
;     for (int i = 0; i < 16; ++i) gg[i] = *(const u32x2*)(gp + (size_t)i * 2 * 3072);
; __device__ __forceinline__ void attn_item(const AttnBufs& T, int type, int b, int h, int qrow0, int NT, LAS char* lds, int tid_) {
;     ...
;             for (int q = 0; q < 4; ++q) { const f32x4 a = scr[d0 * 4 + q];
; #pragma unroll
;                 for (int j = 0; j < 4; ++j) o[d0][q * 4 + j] = a[j] - lam * (o[d0][q * 4 + j] * rli[q * 4 + j]); }
	v_fma_f32 v64, -v32, v96, v64
	v_mul_f32_e32 v32, v33, v86
	v_fma_f32 v65, -v32, v96, v65
	v_mul_f32_e32 v32, v34, v85
	v_fma_f32 v66, -v32, v96, v66
	v_mul_f32_e32 v32, v35, v84
	v_fma_f32 v67, -v32, v96, v67
	v_mul_f32_e32 v32, v36, v83
	v_fma_f32 v68, -v32, v96, v98
	v_mul_f32_e32 v32, v37, v82
	v_fma_f32 v69, -v32, v96, v99
	v_mul_f32_e32 v32, v38, v81
	v_fma_f32 v38, -v32, v96, v100
	v_mul_f32_e32 v32, v39, v80
	v_fma_f32 v39, -v32, v96, v101
	v_mul_f32_e32 v32, v40, v91
	v_fma_f32 v40, -v32, v96, v74
	v_mul_f32_e32 v32, v41, v90
	v_fma_f32 v41, -v32, v96, v75
	v_mul_f32_e32 v32, v42, v89
	v_fma_f32 v42, -v32, v96, v76
	v_mul_f32_e32 v32, v43, v88
	v_fma_f32 v43, -v32, v96, v77
	v_mul_f32_e32 v32, v44, v95
	v_fma_f32 v44, -v32, v96, v70
	v_mul_f32_e32 v32, v45, v94
	v_fma_f32 v45, -v32, v96, v71
	v_mul_f32_e32 v32, v46, v93
	v_fma_f32 v46, -v32, v96, v72
	v_mul_f32_e32 v32, v47, v92
	v_fma_f32 v47, -v96, v32, v73
	global_load_dwordx4 v[32:35], v[136:137], off offset:176
	global_load_dwordx4 v[98:101], v[136:137], off offset:160
	global_load_dwordx4 v[74:77], v[136:137], off offset:144
	global_load_dwordx4 v[70:73], v[136:137], off offset:128
	s_waitcnt vmcnt(0)
	v_fma_f32 v70, -v16, v96, v70
	v_mul_f32_e32 v16, v17, v86
	v_fma_f32 v71, -v16, v96, v71
	v_mul_f32_e32 v16, v18, v85
	v_fma_f32 v72, -v16, v96, v72
	v_mul_f32_e32 v16, v19, v84
	v_fma_f32 v73, -v16, v96, v73
	v_mul_f32_e32 v16, v20, v83
	v_fma_f32 v74, -v16, v96, v74
	v_mul_f32_e32 v16, v21, v82
	v_fma_f32 v75, -v16, v96, v75
	v_mul_f32_e32 v16, v22, v81
	v_fma_f32 v76, -v16, v96, v76
	v_mul_f32_e32 v16, v23, v80
	v_fma_f32 v77, -v16, v96, v77
	v_mul_f32_e32 v16, v24, v91
	v_fma_f32 v78, -v16, v96, v98
	v_mul_f32_e32 v16, v25, v90
	v_fma_f32 v79, -v16, v96, v99
	v_mul_f32_e32 v16, v26, v89
	v_fma_f32 v97, -v16, v96, v100
	v_mul_f32_e32 v16, v27, v88
	v_fma_f32 v98, -v16, v96, v101
	v_mul_f32_e32 v16, v28, v95
	v_fma_f32 v99, -v16, v96, v32
	v_mul_f32_e32 v16, v29, v94
	v_fma_f32 v100, -v16, v96, v33
	v_mul_f32_e32 v16, v30, v93
	v_fma_f32 v101, -v16, v96, v34
	v_mul_f32_e32 v16, v31, v92
	v_fma_f32 v102, -v96, v16, v35
	global_load_dwordx4 v[16:19], v[136:137], off offset:240
	global_load_dwordx4 v[20:23], v[136:137], off offset:224
	global_load_dwordx4 v[24:27], v[136:137], off offset:208
	global_load_dwordx4 v[28:31], v[136:137], off offset:192
	s_waitcnt vmcnt(0)
	v_fma_f32 v87, -v0, v96, v28
	v_mul_f32_e32 v0, v1, v86
	v_fma_f32 v86, -v0, v96, v29
	v_mul_f32_e32 v0, v2, v85
	v_fma_f32 v85, -v0, v96, v30
	v_mul_f32_e32 v0, v3, v84
	v_fma_f32 v84, -v0, v96, v31
	v_mul_f32_e32 v0, v4, v83
	v_fma_f32 v83, -v0, v96, v24
	v_mul_f32_e32 v0, v5, v82
	v_fma_f32 v82, -v0, v96, v25
	v_mul_f32_e32 v0, v6, v81
	v_fma_f32 v81, -v0, v96, v26
	v_mul_f32_e32 v0, v7, v80
	v_fma_f32 v80, -v0, v96, v27
	v_mul_f32_e32 v0, v8, v91
	v_fma_f32 v91, -v0, v96, v20
	v_mul_f32_e32 v0, v9, v90
	v_fma_f32 v90, -v0, v96, v21
	v_mul_f32_e32 v0, v10, v89
	v_fma_f32 v89, -v0, v96, v22
	v_mul_f32_e32 v0, v11, v88
	v_fma_f32 v88, -v0, v96, v23
	v_mul_f32_e32 v0, v12, v95
	v_fma_f32 v95, -v0, v96, v16
	v_mul_f32_e32 v0, v13, v94
	v_fma_f32 v94, -v0, v96, v17
	v_mul_f32_e32 v0, v14, v93
	v_fma_f32 v93, -v0, v96, v18
	v_mul_f32_e32 v0, v15, v92
	v_fma_f32 v92, -v96, v0, v19
	v_lshlrev_b32_e32 v0, 2, v182
	v_and_b32_e32 v96, 0x7c, v0
	v_or_b32_e32 v0, s2, v96
	v_readlane_b32 s2, v251, 46
	v_readlane_b32 s3, v251, 47
	v_lshl_add_u64 v[2:3], s[36:37], 0, v[176:177]
	v_ashrrev_i32_e32 v1, 31, v0
	v_mov_b64_e32 v[4:5], s[2:3]
	v_mad_u64_u32 v[4:5], s[2:3], v2, s4, v[4:5]
	v_readlane_b32 s2, v251, 48
	v_mad_i32_i24 v5, v3, s4, v5
	v_lshlrev_b64 v[0:1], 1, v[0:1]
	v_readlane_b32 s3, v251, 49
	v_lshl_add_u64 v[6:7], v[4:5], 0, v[0:1]
	global_load_dwordx2 v[36:37], v[6:7], off
	v_mov_b64_e32 v[4:5], s[2:3]
	v_mad_u64_u32 v[8:9], s[2:3], v2, s4, v[4:5]
	v_add_co_u32_e32 v2, vcc, s40, v6
	v_mad_i32_i24 v9, v3, s4, v9
	s_nop 0
	v_addc_co_u32_e32 v3, vcc, 0, v7, vcc
	global_load_dwordx2 v[34:35], v[2:3], off
	v_add_co_u32_e32 v2, vcc, s82, v6
	s_mov_b32 s4, 0x9000
	s_nop 0
	v_addc_co_u32_e32 v3, vcc, 0, v7, vcc
	global_load_dwordx2 v[32:33], v[2:3], off
	v_add_co_u32_e32 v2, vcc, s4, v6
	s_mov_b32 s3, 0x21000
	s_nop 0
	v_addc_co_u32_e32 v3, vcc, 0, v7, vcc
	global_load_dwordx2 v[30:31], v[2:3], off
	v_add_co_u32_e32 v2, vcc, s77, v6
	s_mov_b32 s2, 0x2d000
	s_nop 0
	v_addc_co_u32_e32 v3, vcc, 0, v7, vcc
	global_load_dwordx2 v[28:29], v[2:3], off
	v_add_co_u32_e32 v2, vcc, s5, v6
	v_lshl_add_u64 v[0:1], v[8:9], 0, v[0:1]
	s_nop 0
	v_addc_co_u32_e32 v3, vcc, 0, v7, vcc
	global_load_dwordx2 v[26:27], v[2:3], off
	v_add_co_u32_e32 v2, vcc, s85, v6
	s_nop 1
	v_addc_co_u32_e32 v3, vcc, 0, v7, vcc
	global_load_dwordx2 v[24:25], v[2:3], off
	v_add_co_u32_e32 v2, vcc, s20, v6
	s_nop 1
	v_addc_co_u32_e32 v3, vcc, 0, v7, vcc
	global_load_dwordx2 v[22:23], v[2:3], off
	v_add_co_u32_e32 v2, vcc, s76, v6
	s_nop 1
	v_addc_co_u32_e32 v3, vcc, 0, v7, vcc
	global_load_dwordx2 v[20:21], v[2:3], off
	v_add_co_u32_e32 v2, vcc, s21, v6
	s_nop 1
	v_addc_co_u32_e32 v3, vcc, 0, v7, vcc
	global_load_dwordx2 v[18:19], v[2:3], off
	v_add_co_u32_e32 v2, vcc, s92, v6
	s_nop 1
	v_addc_co_u32_e32 v3, vcc, 0, v7, vcc
	global_load_dwordx2 v[16:17], v[2:3], off
	v_add_co_u32_e32 v2, vcc, s3, v6
	s_nop 1
	v_addc_co_u32_e32 v3, vcc, 0, v7, vcc
	global_load_dwordx2 v[14:15], v[2:3], off
	v_add_co_u32_e32 v2, vcc, s91, v6
	s_nop 1
	v_addc_co_u32_e32 v3, vcc, 0, v7, vcc
	global_load_dwordx2 v[12:13], v[2:3], off
	v_add_co_u32_e32 v2, vcc, s33, v6
	s_nop 1
	v_addc_co_u32_e32 v3, vcc, 0, v7, vcc
	global_load_dwordx2 v[10:11], v[2:3], off
	v_add_co_u32_e32 v2, vcc, s94, v6
	s_nop 1
	v_addc_co_u32_e32 v3, vcc, 0, v7, vcc
	global_load_dwordx2 v[4:5], v[2:3], off
	v_add_co_u32_e32 v2, vcc, s2, v6
	s_add_i32 s2, s73, 0
	s_nop 0
	v_addc_co_u32_e32 v3, vcc, 0, v7, vcc
	v_lshlrev_b32_e32 v6, 2, v181
	v_mul_u32_u24_e32 v7, 0x840, v176
	v_add3_u32 v6, s2, v6, v7
	global_load_dwordx2 v[2:3], v[2:3], off
	s_barrier
; #define LAS __attribute__((address_space(3)))
; __device__ __forceinline__ float bf2f(unsigned h) { return __uint_as_float(h << 16); }
; __device__ __forceinline__ unsigned cvt_pk_bf16(float lo, float hi) { unsigned r; asm volatile("v_cvt_pk_bf16_f32 %0, %1, %2" : "=v"(r) : "v"(lo), "v"(hi)); return r; }
; __device__ __forceinline__ int crow(int r, int hi) { return (r & 3) + 8 * (r >> 2) + 4 * hi; }
; template <bool SUBLN>
; __device__ __forceinline__ void attn_out(const AttnBufs& T, f32x16 (&o)[4], int type, int h, size_t orow0, LAS char* lds, int wid, int lane, int r32, int hi) {
;     ...
;     __syncthreads();
;     LAS float* stg = (LAS float*)(lds + wid * 16896);
; #pragma unroll
;     for (int d0 = 0; d0 < 4; ++d0)
; #pragma unroll
;         for (int r = 0; r < 16; ++r) stg[att::crow(r, hi) * 132 + d0 * 32 + r32] = o[d0][r];
;     asm volatile("s_waitcnt lgkmcnt(0)" ::: "memory");
;     f32x4 wsub = {1.f, 1.f, 1.f, 1.f};
;     if (SUBLN) { wsub = *(const f32x4*)(T.subln + c4) * (1.f - T.lam_init); }
; #pragma unroll
;     for (int i = 0; i < 16; ++i) {
;         f32x4 v = *(const LAS f32x4*)(stg + (2 * i + rr) * 132 + c4);
;         if (SUBLN) {
;             float s = (v[0] * v[0] + v[1] * v[1]) + (v[2] * v[2] + v[3] * v[3]);
;             s += __shfl_xor(s, 1); s += __shfl_xor(s, 2); s += __shfl_xor(s, 4); s += __shfl_xor(s, 8); s += __shfl_xor(s, 16);
;             v = v * (rsqrtf(s * (1.f / 128.f) + EPS)) * wsub;
;         }
;         u32x2 w; w.x = cvt_pk_bf16(v[0] * bf2f(gg[i].x & 0xffffu), v[1] * bf2f(gg[i].x >> 16)); w.y = cvt_pk_bf16(v[2] * bf2f(gg[i].y & 0xffffu), v[3] * bf2f(gg[i].y >> 16));
;         *(u32x2*)(op + (size_t)i * 2 * 3072) = w;
;     }
	ds_write2_b32 v6, v48, v64 offset1:32
	ds_write2_b32 v6, v49, v65 offset0:132 offset1:164
	v_add_u32_e32 v7, 0x400, v6
	v_add_u32_e32 v48, 0x1000, v6
	v_add_u32_e32 v49, 0x1400, v6
	ds_write2_b32 v7, v50, v66 offset0:8 offset1:40
	ds_write2_b32 v7, v51, v67 offset0:140 offset1:172
	ds_write2_b32 v48, v52, v68 offset0:32 offset1:64
	ds_write2_b32 v48, v53, v69 offset0:164 offset1:196
	ds_write2_b32 v49, v54, v38 offset0:40 offset1:72
	ds_write2_b32 v49, v55, v39 offset0:172 offset1:204
	v_add_u32_e32 v38, 0x2000, v6
	ds_write2_b32 v38, v56, v40 offset0:64 offset1:96
	ds_write2_b32 v38, v57, v41 offset0:196 offset1:228
	v_add_u32_e32 v39, 0x2400, v6
	v_add_u32_e32 v41, 0x3200, v6
	ds_write2_b32 v39, v58, v42 offset0:72 offset1:104
	ds_write2_b32 v39, v59, v43 offset0:204 offset1:236
	v_add_u32_e32 v40, 0x3000, v6
	ds_write2_b32 v41, v61, v45 offset0:100 offset1:132
	v_add_u32_e32 v41, 0x3400, v6
	v_add_u32_e32 v42, 0x3600, v6
	ds_write2_b32 v40, v60, v44 offset0:96 offset1:128
	ds_write2_b32 v41, v62, v46 offset0:104 offset1:136
	ds_write2_b32 v42, v63, v47 offset0:108 offset1:140
	ds_write2_b32 v6, v70, v87 offset0:64 offset1:96
	ds_write2_b32 v6, v71, v86 offset0:196 offset1:228
	ds_write2_b32 v7, v72, v85 offset0:72 offset1:104
	ds_write2_b32 v7, v73, v84 offset0:204 offset1:236
	ds_write2_b32 v48, v74, v83 offset0:96 offset1:128
	v_add_u32_e32 v7, 0x1200, v6
	ds_write2_b32 v7, v75, v82 offset0:100 offset1:132
	ds_write2_b32 v49, v76, v81 offset0:104 offset1:136
	v_add_u32_e32 v7, 0x1600, v6
	ds_write2_b32 v7, v77, v80 offset0:108 offset1:140
	ds_write2_b32 v38, v78, v91 offset0:128 offset1:160
	ds_write2_b32 v39, v79, v90 offset0:4 offset1:36
	ds_write2_b32 v39, v97, v89 offset0:136 offset1:168
	v_add_u32_e32 v7, 0x2800, v6
	v_add_u32_e32 v6, 0x3800, v6
	ds_write2_b32 v7, v98, v88 offset0:12 offset1:44
	ds_write2_b32 v40, v99, v95 offset0:160 offset1:192
	ds_write2_b32 v41, v100, v94 offset0:36 offset1:68
	ds_write2_b32 v41, v101, v93 offset0:168 offset1:200
	ds_write2_b32 v6, v102, v92 offset0:44 offset1:76
	s_waitcnt lgkmcnt(0)
	v_lshlrev_b32_e32 v43, 2, v96
	global_load_dwordx4 v[38:41], v43, s[26:27]
	v_xor_b32_e32 v44, 16, v228
	s_waitcnt vmcnt(0)
	v_pk_mul_f32 v[8:9], v[162:163], v[38:39]
	v_and_b32_e32 v39, 64, v228
	v_xor_b32_e32 v38, 1, v228
	v_add_u32_e32 v42, 64, v39
	v_cmp_lt_i32_e32 vcc, v38, v42
	v_xor_b32_e32 v39, 2, v228
	v_pk_mul_f32 v[6:7], v[160:161], v[40:41]
	v_cndmask_b32_e32 v38, v228, v38, vcc
	v_cmp_lt_i32_e32 vcc, v39, v42
	v_xor_b32_e32 v40, 4, v228
	v_xor_b32_e32 v41, 8, v228
	v_cndmask_b32_e32 v39, v228, v39, vcc
	v_cmp_lt_i32_e32 vcc, v40, v42
	v_lshlrev_b32_e32 v38, 2, v38
	v_lshlrev_b32_e32 v39, 2, v39
	v_cndmask_b32_e32 v40, v228, v40, vcc
	v_cmp_lt_i32_e32 vcc, v41, v42
	v_lshlrev_b32_e32 v40, 2, v40
	s_nop 0
	v_cndmask_b32_e32 v41, v228, v41, vcc
	v_cmp_lt_i32_e32 vcc, v44, v42
	v_lshlrev_b32_e32 v41, 2, v41
	s_nop 0
	v_cndmask_b32_e32 v42, v228, v44, vcc
	v_mul_u32_u24_e32 v44, 0x210, v176
	v_add3_u32 v43, s2, v43, v44
	ds_read_b128 v[44:47], v43
	v_lshlrev_b32_e32 v42, 2, v42
	s_mov_b32 s2, 0x800000
	s_waitcnt lgkmcnt(0)
	v_pk_mul_f32 v[48:49], v[46:47], v[46:47]
	v_pk_mul_f32 v[50:51], v[44:45], v[44:45]
	s_nop 0
	v_pk_mov_b32 v[52:53], v[50:51], v[48:49] op_sel:[1,0]
	v_mov_b32_e32 v51, v49
	v_pk_add_f32 v[48:49], v[52:53], v[50:51]
	s_nop 0
	v_add_f32_e32 v48, v48, v49
	ds_bpermute_b32 v49, v38, v48
	s_waitcnt lgkmcnt(0)
	v_add_f32_e32 v48, v48, v49
	ds_bpermute_b32 v49, v39, v48
	s_waitcnt lgkmcnt(0)
	v_add_f32_e32 v48, v48, v49
	ds_bpermute_b32 v49, v40, v48
	s_waitcnt lgkmcnt(0)
	v_add_f32_e32 v48, v48, v49
	ds_bpermute_b32 v49, v41, v48
	s_waitcnt lgkmcnt(0)
	v_add_f32_e32 v48, v48, v49
	ds_bpermute_b32 v49, v42, v48
	s_waitcnt lgkmcnt(0)
	v_add_f32_e32 v48, v48, v49
	v_fmamk_f32 v48, v48, 0x3c000000, v178
	v_cmp_gt_f32_e32 vcc, s2, v48
	v_mul_f32_e32 v49, 0x4b800000, v48
	s_nop 0
	v_cndmask_b32_e32 v48, v48, v49, vcc
	v_rsq_f32_e32 v48, v48
	s_nop 0
	v_mul_f32_e32 v49, 0x45800000, v48
	v_cndmask_b32_e32 v48, v48, v49, vcc
	v_pk_mul_f32 v[44:45], v[44:45], v[48:49] op_sel_hi:[1,0]
	v_pk_mul_f32 v[46:47], v[46:47], v[48:49] op_sel_hi:[1,0]
	v_pk_mul_f32 v[44:45], v[8:9], v[44:45]
	v_lshlrev_b32_e32 v48, 16, v36
	v_and_b32_e32 v36, 0xffff0000, v36
	v_mul_f32_e32 v44, v44, v48
	v_mul_f32_e32 v36, v45, v36
	v_pk_mul_f32 v[46:47], v[6:7], v[46:47]
	v_cvt_pk_bf16_f32 v36, v44, v36
	v_lshlrev_b32_e32 v44, 16, v37
	v_and_b32_e32 v37, 0xffff0000, v37
	v_mul_f32_e32 v44, v46, v44
	v_mul_f32_e32 v37, v47, v37
	v_cvt_pk_bf16_f32 v37, v44, v37
	ds_read_b128 v[44:47], v43 offset:1056
	global_store_dwordx2 v[0:1], v[36:37], off
	s_waitcnt lgkmcnt(0)
	v_pk_mul_f32 v[36:37], v[46:47], v[46:47]
	v_pk_mul_f32 v[48:49], v[44:45], v[44:45]
	s_nop 0
	v_pk_mov_b32 v[50:51], v[48:49], v[36:37] op_sel:[1,0]
	v_mov_b32_e32 v49, v37
	v_pk_add_f32 v[36:37], v[50:51], v[48:49]
	s_nop 0
	v_add_f32_e32 v36, v36, v37
	ds_bpermute_b32 v37, v38, v36
	s_waitcnt lgkmcnt(0)
	v_add_f32_e32 v36, v36, v37
	ds_bpermute_b32 v37, v39, v36
	s_waitcnt lgkmcnt(0)
	v_add_f32_e32 v36, v36, v37
	ds_bpermute_b32 v37, v40, v36
	s_waitcnt lgkmcnt(0)
	v_add_f32_e32 v36, v36, v37
	ds_bpermute_b32 v37, v41, v36
	s_waitcnt lgkmcnt(0)
	v_add_f32_e32 v36, v36, v37
	ds_bpermute_b32 v37, v42, v36
	s_waitcnt lgkmcnt(0)
; #define LAS __attribute__((address_space(3)))
; __device__ __forceinline__ float bf2f(unsigned h) { return __uint_as_float(h << 16); }
; __device__ __forceinline__ unsigned cvt_pk_bf16(float lo, float hi) { unsigned r; asm volatile("v_cvt_pk_bf16_f32 %0, %1, %2" : "=v"(r) : "v"(lo), "v"(hi)); return r; }
; template <bool SUBLN>
; __device__ __forceinline__ void attn_out(const AttnBufs& T, f32x16 (&o)[4], int type, int h, size_t orow0, LAS char* lds, int wid, int lane, int r32, int hi) {
;     ...
;     for (int i = 0; i < 16; ++i) {
;         f32x4 v = *(const LAS f32x4*)(stg + (2 * i + rr) * 132 + c4);
;         if (SUBLN) {
;             float s = (v[0] * v[0] + v[1] * v[1]) + (v[2] * v[2] + v[3] * v[3]);
;             s += __shfl_xor(s, 1); s += __shfl_xor(s, 2); s += __shfl_xor(s, 4); s += __shfl_xor(s, 8); s += __shfl_xor(s, 16);
;             v = v * (rsqrtf(s * (1.f / 128.f) + EPS)) * wsub;
;         }
;         u32x2 w; w.x = cvt_pk_bf16(v[0] * bf2f(gg[i].x & 0xffffu), v[1] * bf2f(gg[i].x >> 16)); w.y = cvt_pk_bf16(v[2] * bf2f(gg[i].y & 0xffffu), v[3] * bf2f(gg[i].y >> 16));
;         *(u32x2*)(op + (size_t)i * 2 * 3072) = w;
;     }
	v_add_f32_e32 v36, v36, v37
	v_fmamk_f32 v36, v36, 0x3c000000, v178
	v_cmp_gt_f32_e32 vcc, s2, v36
	v_mul_f32_e32 v37, 0x4b800000, v36
	s_nop 0
	v_cndmask_b32_e32 v36, v36, v37, vcc
	v_rsq_f32_e32 v36, v36
	s_nop 0
	v_mul_f32_e32 v37, 0x45800000, v36
	v_cndmask_b32_e32 v36, v36, v37, vcc
	v_pk_mul_f32 v[44:45], v[44:45], v[36:37] op_sel_hi:[1,0]
	v_pk_mul_f32 v[36:37], v[46:47], v[36:37] op_sel_hi:[1,0]
	v_pk_mul_f32 v[44:45], v[8:9], v[44:45]
	v_lshlrev_b32_e32 v46, 16, v34
	v_and_b32_e32 v34, 0xffff0000, v34
	v_mul_f32_e32 v44, v44, v46
	v_mul_f32_e32 v34, v45, v34
	v_pk_mul_f32 v[36:37], v[6:7], v[36:37]
	v_cvt_pk_bf16_f32 v34, v44, v34
	v_lshlrev_b32_e32 v44, 16, v35
	v_and_b32_e32 v35, 0xffff0000, v35
	v_mul_f32_e32 v36, v36, v44
	v_mul_f32_e32 v35, v37, v35
	v_cvt_pk_bf16_f32 v35, v36, v35
	v_add_co_u32_e32 v36, vcc, s40, v0
	s_nop 1
	v_addc_co_u32_e32 v37, vcc, 0, v1, vcc
	global_store_dwordx2 v[36:37], v[34:35], off
	ds_read_b128 v[34:37], v43 offset:2112
	s_waitcnt lgkmcnt(0)
	v_pk_mul_f32 v[44:45], v[36:37], v[36:37]
	v_pk_mul_f32 v[46:47], v[34:35], v[34:35]
	s_nop 0
	v_pk_mov_b32 v[48:49], v[46:47], v[44:45] op_sel:[1,0]
	v_mov_b32_e32 v47, v45
	v_pk_add_f32 v[44:45], v[48:49], v[46:47]
	s_nop 0
	v_add_f32_e32 v44, v44, v45
	ds_bpermute_b32 v45, v38, v44
	s_waitcnt lgkmcnt(0)
	v_add_f32_e32 v44, v44, v45
	ds_bpermute_b32 v45, v39, v44
	s_waitcnt lgkmcnt(0)
	v_add_f32_e32 v44, v44, v45
	ds_bpermute_b32 v45, v40, v44
	s_waitcnt lgkmcnt(0)
	v_add_f32_e32 v44, v44, v45
	ds_bpermute_b32 v45, v41, v44
	s_waitcnt lgkmcnt(0)
	v_add_f32_e32 v44, v44, v45
	ds_bpermute_b32 v45, v42, v44
	s_waitcnt lgkmcnt(0)
	v_add_f32_e32 v44, v44, v45
	v_fmamk_f32 v44, v44, 0x3c000000, v178
	v_cmp_gt_f32_e32 vcc, s2, v44
	v_mul_f32_e32 v45, 0x4b800000, v44
	s_nop 0
	v_cndmask_b32_e32 v44, v44, v45, vcc
	v_rsq_f32_e32 v44, v44
	s_nop 0
	v_mul_f32_e32 v45, 0x45800000, v44
	v_cndmask_b32_e32 v44, v44, v45, vcc
	v_pk_mul_f32 v[34:35], v[34:35], v[44:45] op_sel_hi:[1,0]
	v_pk_mul_f32 v[36:37], v[36:37], v[44:45] op_sel_hi:[1,0]
	v_pk_mul_f32 v[34:35], v[8:9], v[34:35]
	v_lshlrev_b32_e32 v44, 16, v32
	v_and_b32_e32 v32, 0xffff0000, v32
	v_mul_f32_e32 v34, v34, v44
	v_mul_f32_e32 v32, v35, v32
	v_pk_mul_f32 v[36:37], v[6:7], v[36:37]
	v_cvt_pk_bf16_f32 v32, v34, v32
	v_lshlrev_b32_e32 v34, 16, v33
	v_and_b32_e32 v33, 0xffff0000, v33
	v_mul_f32_e32 v34, v36, v34
	v_mul_f32_e32 v33, v37, v33
	v_cvt_pk_bf16_f32 v33, v34, v33
	v_add_co_u32_e32 v34, vcc, s82, v0
	s_nop 1
	v_addc_co_u32_e32 v35, vcc, 0, v1, vcc
	global_store_dwordx2 v[34:35], v[32:33], off
	ds_read_b128 v[32:35], v43 offset:3168
	s_waitcnt lgkmcnt(0)
	v_pk_mul_f32 v[36:37], v[34:35], v[34:35]
	v_pk_mul_f32 v[44:45], v[32:33], v[32:33]
	s_nop 0
	v_pk_mov_b32 v[46:47], v[44:45], v[36:37] op_sel:[1,0]
	v_mov_b32_e32 v45, v37
	v_pk_add_f32 v[36:37], v[46:47], v[44:45]
	s_nop 0
	v_add_f32_e32 v36, v36, v37
	ds_bpermute_b32 v37, v38, v36
	s_waitcnt lgkmcnt(0)
	v_add_f32_e32 v36, v36, v37
	ds_bpermute_b32 v37, v39, v36
	s_waitcnt lgkmcnt(0)
	v_add_f32_e32 v36, v36, v37
	ds_bpermute_b32 v37, v40, v36
	s_waitcnt lgkmcnt(0)
	v_add_f32_e32 v36, v36, v37
	ds_bpermute_b32 v37, v41, v36
	s_waitcnt lgkmcnt(0)
	v_add_f32_e32 v36, v36, v37
	ds_bpermute_b32 v37, v42, v36
	s_waitcnt lgkmcnt(0)
	v_add_f32_e32 v36, v36, v37
	v_fmamk_f32 v36, v36, 0x3c000000, v178
	v_cmp_gt_f32_e32 vcc, s2, v36
	v_mul_f32_e32 v37, 0x4b800000, v36
	s_nop 0
	v_cndmask_b32_e32 v36, v36, v37, vcc
	v_rsq_f32_e32 v36, v36
	s_nop 0
	v_mul_f32_e32 v37, 0x45800000, v36
	v_cndmask_b32_e32 v36, v36, v37, vcc
	v_pk_mul_f32 v[32:33], v[32:33], v[36:37] op_sel_hi:[1,0]
	v_pk_mul_f32 v[34:35], v[34:35], v[36:37] op_sel_hi:[1,0]
	v_pk_mul_f32 v[32:33], v[8:9], v[32:33]
	v_lshlrev_b32_e32 v36, 16, v30
	v_and_b32_e32 v30, 0xffff0000, v30
	v_mul_f32_e32 v32, v32, v36
	v_mul_f32_e32 v30, v33, v30
	v_pk_mul_f32 v[34:35], v[6:7], v[34:35]
	v_cvt_pk_bf16_f32 v30, v32, v30
	v_lshlrev_b32_e32 v32, 16, v31
	v_and_b32_e32 v31, 0xffff0000, v31
	v_mul_f32_e32 v32, v34, v32
	v_mul_f32_e32 v31, v35, v31
	v_cvt_pk_bf16_f32 v31, v32, v31
	v_add_co_u32_e32 v32, vcc, s4, v0
	s_nop 1
	v_addc_co_u32_e32 v33, vcc, 0, v1, vcc
	global_store_dwordx2 v[32:33], v[30:31], off
	ds_read_b128 v[30:33], v43 offset:4224
	s_waitcnt lgkmcnt(0)
	v_pk_mul_f32 v[34:35], v[32:33], v[32:33]
	v_pk_mul_f32 v[36:37], v[30:31], v[30:31]
	s_nop 0
	v_pk_mov_b32 v[44:45], v[36:37], v[34:35] op_sel:[1,0]
	v_mov_b32_e32 v37, v35
	v_pk_add_f32 v[34:35], v[44:45], v[36:37]
	s_nop 0
	v_add_f32_e32 v34, v34, v35
	ds_bpermute_b32 v35, v38, v34
	s_waitcnt lgkmcnt(0)
	v_add_f32_e32 v34, v34, v35
	ds_bpermute_b32 v35, v39, v34
	s_waitcnt lgkmcnt(0)
	v_add_f32_e32 v34, v34, v35
	ds_bpermute_b32 v35, v40, v34
	s_waitcnt lgkmcnt(0)
	v_add_f32_e32 v34, v34, v35
	ds_bpermute_b32 v35, v41, v34
	s_waitcnt lgkmcnt(0)
	v_add_f32_e32 v34, v34, v35
	ds_bpermute_b32 v35, v42, v34
	s_waitcnt lgkmcnt(0)
	v_add_f32_e32 v34, v34, v35
	v_fmamk_f32 v34, v34, 0x3c000000, v178
	v_cmp_gt_f32_e32 vcc, s2, v34
	v_mul_f32_e32 v35, 0x4b800000, v34
	s_nop 0
	v_cndmask_b32_e32 v34, v34, v35, vcc
	v_rsq_f32_e32 v34, v34
	s_nop 0
	v_mul_f32_e32 v35, 0x45800000, v34
	v_cndmask_b32_e32 v34, v34, v35, vcc
	v_pk_mul_f32 v[30:31], v[30:31], v[34:35] op_sel_hi:[1,0]
	v_pk_mul_f32 v[32:33], v[32:33], v[34:35] op_sel_hi:[1,0]
	v_pk_mul_f32 v[30:31], v[8:9], v[30:31]
	v_lshlrev_b32_e32 v34, 16, v28
	v_and_b32_e32 v28, 0xffff0000, v28
	v_mul_f32_e32 v30, v30, v34
	v_mul_f32_e32 v28, v31, v28
	v_pk_mul_f32 v[32:33], v[6:7], v[32:33]
	v_cvt_pk_bf16_f32 v28, v30, v28
	v_lshlrev_b32_e32 v30, 16, v29
	v_and_b32_e32 v29, 0xffff0000, v29
	v_mul_f32_e32 v30, v32, v30
	v_mul_f32_e32 v29, v33, v29
	v_cvt_pk_bf16_f32 v29, v30, v29
	v_add_co_u32_e32 v30, vcc, s77, v0
	s_nop 1
	v_addc_co_u32_e32 v31, vcc, 0, v1, vcc
	global_store_dwordx2 v[30:31], v[28:29], off
	ds_read_b128 v[28:31], v43 offset:5280
	s_waitcnt lgkmcnt(0)
; #define LAS __attribute__((address_space(3)))
; __device__ __forceinline__ float bf2f(unsigned h) { return __uint_as_float(h << 16); }
; __device__ __forceinline__ unsigned cvt_pk_bf16(float lo, float hi) { unsigned r; asm volatile("v_cvt_pk_bf16_f32 %0, %1, %2" : "=v"(r) : "v"(lo), "v"(hi)); return r; }
; template <bool SUBLN>
; __device__ __forceinline__ void attn_out(const AttnBufs& T, f32x16 (&o)[4], int type, int h, size_t orow0, LAS char* lds, int wid, int lane, int r32, int hi) {
;     ...
;     for (int i = 0; i < 16; ++i) {
;         f32x4 v = *(const LAS f32x4*)(stg + (2 * i + rr) * 132 + c4);
;         if (SUBLN) {
;             float s = (v[0] * v[0] + v[1] * v[1]) + (v[2] * v[2] + v[3] * v[3]);
;             s += __shfl_xor(s, 1); s += __shfl_xor(s, 2); s += __shfl_xor(s, 4); s += __shfl_xor(s, 8); s += __shfl_xor(s, 16);
;             v = v * (rsqrtf(s * (1.f / 128.f) + EPS)) * wsub;
;         }
;         u32x2 w; w.x = cvt_pk_bf16(v[0] * bf2f(gg[i].x & 0xffffu), v[1] * bf2f(gg[i].x >> 16)); w.y = cvt_pk_bf16(v[2] * bf2f(gg[i].y & 0xffffu), v[3] * bf2f(gg[i].y >> 16));
;         *(u32x2*)(op + (size_t)i * 2 * 3072) = w;
;     }
	v_pk_mul_f32 v[32:33], v[30:31], v[30:31]
	v_pk_mul_f32 v[34:35], v[28:29], v[28:29]
	s_nop 0
	v_pk_mov_b32 v[36:37], v[34:35], v[32:33] op_sel:[1,0]
	v_mov_b32_e32 v35, v33
	v_pk_add_f32 v[32:33], v[36:37], v[34:35]
	s_nop 0
	v_add_f32_e32 v32, v32, v33
	ds_bpermute_b32 v33, v38, v32
	s_waitcnt lgkmcnt(0)
	v_add_f32_e32 v32, v32, v33
	ds_bpermute_b32 v33, v39, v32
	s_waitcnt lgkmcnt(0)
	v_add_f32_e32 v32, v32, v33
	ds_bpermute_b32 v33, v40, v32
	s_waitcnt lgkmcnt(0)
	v_add_f32_e32 v32, v32, v33
	ds_bpermute_b32 v33, v41, v32
	s_waitcnt lgkmcnt(0)
	v_add_f32_e32 v32, v32, v33
	ds_bpermute_b32 v33, v42, v32
	s_waitcnt lgkmcnt(0)
	v_add_f32_e32 v32, v32, v33
	v_fmamk_f32 v32, v32, 0x3c000000, v178
	v_cmp_gt_f32_e32 vcc, s2, v32
	v_mul_f32_e32 v33, 0x4b800000, v32
	s_nop 0
	v_cndmask_b32_e32 v32, v32, v33, vcc
	v_rsq_f32_e32 v32, v32
	s_nop 0
	v_mul_f32_e32 v33, 0x45800000, v32
	v_cndmask_b32_e32 v32, v32, v33, vcc
	v_pk_mul_f32 v[28:29], v[28:29], v[32:33] op_sel_hi:[1,0]
	v_pk_mul_f32 v[30:31], v[30:31], v[32:33] op_sel_hi:[1,0]
	v_pk_mul_f32 v[28:29], v[8:9], v[28:29]
	v_lshlrev_b32_e32 v32, 16, v26
	v_and_b32_e32 v26, 0xffff0000, v26
	v_mul_f32_e32 v28, v28, v32
	v_mul_f32_e32 v26, v29, v26
	v_pk_mul_f32 v[30:31], v[6:7], v[30:31]
	v_cvt_pk_bf16_f32 v26, v28, v26
	v_lshlrev_b32_e32 v28, 16, v27
	v_and_b32_e32 v27, 0xffff0000, v27
	v_mul_f32_e32 v28, v30, v28
	v_mul_f32_e32 v27, v31, v27
	v_cvt_pk_bf16_f32 v27, v28, v27
	v_add_co_u32_e32 v28, vcc, s5, v0
	s_nop 1
	v_addc_co_u32_e32 v29, vcc, 0, v1, vcc
	global_store_dwordx2 v[28:29], v[26:27], off
	ds_read_b128 v[26:29], v43 offset:6336
	s_waitcnt lgkmcnt(0)
	v_pk_mul_f32 v[30:31], v[28:29], v[28:29]
	v_pk_mul_f32 v[32:33], v[26:27], v[26:27]
	s_nop 0
	v_pk_mov_b32 v[34:35], v[32:33], v[30:31] op_sel:[1,0]
	v_mov_b32_e32 v33, v31
	v_pk_add_f32 v[30:31], v[34:35], v[32:33]
	s_nop 0
	v_add_f32_e32 v30, v30, v31
	ds_bpermute_b32 v31, v38, v30
	s_waitcnt lgkmcnt(0)
	v_add_f32_e32 v30, v30, v31
	ds_bpermute_b32 v31, v39, v30
	s_waitcnt lgkmcnt(0)
	v_add_f32_e32 v30, v30, v31
	ds_bpermute_b32 v31, v40, v30
	s_waitcnt lgkmcnt(0)
	v_add_f32_e32 v30, v30, v31
	ds_bpermute_b32 v31, v41, v30
	s_waitcnt lgkmcnt(0)
	v_add_f32_e32 v30, v30, v31
	ds_bpermute_b32 v31, v42, v30
	s_waitcnt lgkmcnt(0)
	v_add_f32_e32 v30, v30, v31
	v_fmamk_f32 v30, v30, 0x3c000000, v178
	v_cmp_gt_f32_e32 vcc, s2, v30
	v_mul_f32_e32 v31, 0x4b800000, v30
	s_nop 0
	v_cndmask_b32_e32 v30, v30, v31, vcc
	v_rsq_f32_e32 v30, v30
	s_nop 0
	v_mul_f32_e32 v31, 0x45800000, v30
	v_cndmask_b32_e32 v30, v30, v31, vcc
	v_pk_mul_f32 v[26:27], v[26:27], v[30:31] op_sel_hi:[1,0]
	v_pk_mul_f32 v[28:29], v[28:29], v[30:31] op_sel_hi:[1,0]
	v_pk_mul_f32 v[26:27], v[8:9], v[26:27]
	v_lshlrev_b32_e32 v30, 16, v24
	v_and_b32_e32 v24, 0xffff0000, v24
	v_mul_f32_e32 v26, v26, v30
	v_mul_f32_e32 v24, v27, v24
	v_pk_mul_f32 v[28:29], v[6:7], v[28:29]
	v_cvt_pk_bf16_f32 v24, v26, v24
	v_lshlrev_b32_e32 v26, 16, v25
	v_and_b32_e32 v25, 0xffff0000, v25
	v_mul_f32_e32 v26, v28, v26
	v_mul_f32_e32 v25, v29, v25
	v_cvt_pk_bf16_f32 v25, v26, v25
	v_add_co_u32_e32 v26, vcc, s85, v0
	s_nop 1
	v_addc_co_u32_e32 v27, vcc, 0, v1, vcc
	global_store_dwordx2 v[26:27], v[24:25], off
	ds_read_b128 v[24:27], v43 offset:7392
	s_waitcnt lgkmcnt(0)
	v_pk_mul_f32 v[28:29], v[26:27], v[26:27]
	v_pk_mul_f32 v[30:31], v[24:25], v[24:25]
	s_nop 0
	v_pk_mov_b32 v[32:33], v[30:31], v[28:29] op_sel:[1,0]
	v_mov_b32_e32 v31, v29
	v_pk_add_f32 v[28:29], v[32:33], v[30:31]
	s_nop 0
	v_add_f32_e32 v28, v28, v29
	ds_bpermute_b32 v29, v38, v28
	s_waitcnt lgkmcnt(0)
	v_add_f32_e32 v28, v28, v29
	ds_bpermute_b32 v29, v39, v28
	s_waitcnt lgkmcnt(0)
	v_add_f32_e32 v28, v28, v29
	ds_bpermute_b32 v29, v40, v28
	s_waitcnt lgkmcnt(0)
	v_add_f32_e32 v28, v28, v29
	ds_bpermute_b32 v29, v41, v28
	s_waitcnt lgkmcnt(0)
	v_add_f32_e32 v28, v28, v29
	ds_bpermute_b32 v29, v42, v28
	s_waitcnt lgkmcnt(0)
	v_add_f32_e32 v28, v28, v29
	v_fmamk_f32 v28, v28, 0x3c000000, v178
	v_cmp_gt_f32_e32 vcc, s2, v28
	v_mul_f32_e32 v29, 0x4b800000, v28
	s_nop 0
	v_cndmask_b32_e32 v28, v28, v29, vcc
	v_rsq_f32_e32 v28, v28
	s_nop 0
	v_mul_f32_e32 v29, 0x45800000, v28
	v_cndmask_b32_e32 v28, v28, v29, vcc
	v_pk_mul_f32 v[24:25], v[24:25], v[28:29] op_sel_hi:[1,0]
	v_pk_mul_f32 v[26:27], v[26:27], v[28:29] op_sel_hi:[1,0]
	v_pk_mul_f32 v[24:25], v[8:9], v[24:25]
	v_lshlrev_b32_e32 v28, 16, v22
	v_and_b32_e32 v22, 0xffff0000, v22
	v_mul_f32_e32 v24, v24, v28
	v_mul_f32_e32 v22, v25, v22
	v_pk_mul_f32 v[26:27], v[6:7], v[26:27]
	v_cvt_pk_bf16_f32 v22, v24, v22
	v_lshlrev_b32_e32 v24, 16, v23
	v_and_b32_e32 v23, 0xffff0000, v23
	v_mul_f32_e32 v24, v26, v24
	v_mul_f32_e32 v23, v27, v23
	v_cvt_pk_bf16_f32 v23, v24, v23
	v_add_co_u32_e32 v24, vcc, s20, v0
	s_nop 1
	v_addc_co_u32_e32 v25, vcc, 0, v1, vcc
	global_store_dwordx2 v[24:25], v[22:23], off
	ds_read_b128 v[22:25], v43 offset:8448
	s_waitcnt lgkmcnt(0)
	v_pk_mul_f32 v[26:27], v[24:25], v[24:25]
	v_pk_mul_f32 v[28:29], v[22:23], v[22:23]
	s_nop 0
	v_pk_mov_b32 v[30:31], v[28:29], v[26:27] op_sel:[1,0]
	v_mov_b32_e32 v29, v27
	v_pk_add_f32 v[26:27], v[30:31], v[28:29]
	s_nop 0
	v_add_f32_e32 v26, v26, v27
	ds_bpermute_b32 v27, v38, v26
	s_waitcnt lgkmcnt(0)
	v_add_f32_e32 v26, v26, v27
	ds_bpermute_b32 v27, v39, v26
	s_waitcnt lgkmcnt(0)
	v_add_f32_e32 v26, v26, v27
	ds_bpermute_b32 v27, v40, v26
	s_waitcnt lgkmcnt(0)
	v_add_f32_e32 v26, v26, v27
	ds_bpermute_b32 v27, v41, v26
	s_waitcnt lgkmcnt(0)
	v_add_f32_e32 v26, v26, v27
	ds_bpermute_b32 v27, v42, v26
	s_waitcnt lgkmcnt(0)
; #define LAS __attribute__((address_space(3)))
; __device__ __forceinline__ float bf2f(unsigned h) { return __uint_as_float(h << 16); }
; __device__ __forceinline__ unsigned cvt_pk_bf16(float lo, float hi) { unsigned r; asm volatile("v_cvt_pk_bf16_f32 %0, %1, %2" : "=v"(r) : "v"(lo), "v"(hi)); return r; }
; template <bool SUBLN>
; __device__ __forceinline__ void attn_out(const AttnBufs& T, f32x16 (&o)[4], int type, int h, size_t orow0, LAS char* lds, int wid, int lane, int r32, int hi) {
;     ...
;     for (int i = 0; i < 16; ++i) {
;         f32x4 v = *(const LAS f32x4*)(stg + (2 * i + rr) * 132 + c4);
;         if (SUBLN) {
;             float s = (v[0] * v[0] + v[1] * v[1]) + (v[2] * v[2] + v[3] * v[3]);
;             s += __shfl_xor(s, 1); s += __shfl_xor(s, 2); s += __shfl_xor(s, 4); s += __shfl_xor(s, 8); s += __shfl_xor(s, 16);
;             v = v * (rsqrtf(s * (1.f / 128.f) + EPS)) * wsub;
;         }
;         u32x2 w; w.x = cvt_pk_bf16(v[0] * bf2f(gg[i].x & 0xffffu), v[1] * bf2f(gg[i].x >> 16)); w.y = cvt_pk_bf16(v[2] * bf2f(gg[i].y & 0xffffu), v[3] * bf2f(gg[i].y >> 16));
;         *(u32x2*)(op + (size_t)i * 2 * 3072) = w;
;     }
	v_add_f32_e32 v26, v26, v27
	v_fmamk_f32 v26, v26, 0x3c000000, v178
	v_cmp_gt_f32_e32 vcc, s2, v26
	v_mul_f32_e32 v27, 0x4b800000, v26
	s_nop 0
	v_cndmask_b32_e32 v26, v26, v27, vcc
	v_rsq_f32_e32 v26, v26
	s_nop 0
	v_mul_f32_e32 v27, 0x45800000, v26
	v_cndmask_b32_e32 v26, v26, v27, vcc
	v_pk_mul_f32 v[22:23], v[22:23], v[26:27] op_sel_hi:[1,0]
	v_pk_mul_f32 v[24:25], v[24:25], v[26:27] op_sel_hi:[1,0]
	v_pk_mul_f32 v[22:23], v[8:9], v[22:23]
	v_lshlrev_b32_e32 v26, 16, v20
	v_and_b32_e32 v20, 0xffff0000, v20
	v_mul_f32_e32 v22, v22, v26
	v_mul_f32_e32 v20, v23, v20
	v_pk_mul_f32 v[24:25], v[6:7], v[24:25]
	v_cvt_pk_bf16_f32 v20, v22, v20
	v_lshlrev_b32_e32 v22, 16, v21
	v_and_b32_e32 v21, 0xffff0000, v21
	v_mul_f32_e32 v22, v24, v22
	v_mul_f32_e32 v21, v25, v21
	v_cvt_pk_bf16_f32 v21, v22, v21
	v_add_co_u32_e32 v22, vcc, s76, v0
	s_nop 1
	v_addc_co_u32_e32 v23, vcc, 0, v1, vcc
	global_store_dwordx2 v[22:23], v[20:21], off
	ds_read_b128 v[20:23], v43 offset:9504
	s_waitcnt lgkmcnt(0)
	v_pk_mul_f32 v[24:25], v[22:23], v[22:23]
	v_pk_mul_f32 v[26:27], v[20:21], v[20:21]
	s_nop 0
	v_pk_mov_b32 v[28:29], v[26:27], v[24:25] op_sel:[1,0]
	v_mov_b32_e32 v27, v25
	v_pk_add_f32 v[24:25], v[28:29], v[26:27]
	s_nop 0
	v_add_f32_e32 v24, v24, v25
	ds_bpermute_b32 v25, v38, v24
	s_waitcnt lgkmcnt(0)
	v_add_f32_e32 v24, v24, v25
	ds_bpermute_b32 v25, v39, v24
	s_waitcnt lgkmcnt(0)
	v_add_f32_e32 v24, v24, v25
	ds_bpermute_b32 v25, v40, v24
	s_waitcnt lgkmcnt(0)
	v_add_f32_e32 v24, v24, v25
	ds_bpermute_b32 v25, v41, v24
	s_waitcnt lgkmcnt(0)
	v_add_f32_e32 v24, v24, v25
	ds_bpermute_b32 v25, v42, v24
	s_waitcnt lgkmcnt(0)
	v_add_f32_e32 v24, v24, v25
	v_fmamk_f32 v24, v24, 0x3c000000, v178
	v_cmp_gt_f32_e32 vcc, s2, v24
	v_mul_f32_e32 v25, 0x4b800000, v24
	s_nop 0
	v_cndmask_b32_e32 v24, v24, v25, vcc
	v_rsq_f32_e32 v24, v24
	s_nop 0
	v_mul_f32_e32 v25, 0x45800000, v24
	v_cndmask_b32_e32 v24, v24, v25, vcc
	v_pk_mul_f32 v[20:21], v[20:21], v[24:25] op_sel_hi:[1,0]
	v_pk_mul_f32 v[22:23], v[22:23], v[24:25] op_sel_hi:[1,0]
	v_pk_mul_f32 v[20:21], v[8:9], v[20:21]
	v_lshlrev_b32_e32 v24, 16, v18
	v_and_b32_e32 v18, 0xffff0000, v18
	v_mul_f32_e32 v20, v20, v24
	v_mul_f32_e32 v18, v21, v18
	v_pk_mul_f32 v[22:23], v[6:7], v[22:23]
	v_cvt_pk_bf16_f32 v18, v20, v18
	v_lshlrev_b32_e32 v20, 16, v19
	v_and_b32_e32 v19, 0xffff0000, v19
	v_mul_f32_e32 v20, v22, v20
	v_mul_f32_e32 v19, v23, v19
	v_cvt_pk_bf16_f32 v19, v20, v19
	v_add_co_u32_e32 v20, vcc, s21, v0
	s_nop 1
	v_addc_co_u32_e32 v21, vcc, 0, v1, vcc
	global_store_dwordx2 v[20:21], v[18:19], off
	ds_read_b128 v[18:21], v43 offset:10560
	s_waitcnt lgkmcnt(0)
	v_pk_mul_f32 v[22:23], v[20:21], v[20:21]
	v_pk_mul_f32 v[24:25], v[18:19], v[18:19]
	s_nop 0
	v_pk_mov_b32 v[26:27], v[24:25], v[22:23] op_sel:[1,0]
	v_mov_b32_e32 v25, v23
	v_pk_add_f32 v[22:23], v[26:27], v[24:25]
	s_nop 0
	v_add_f32_e32 v22, v22, v23
	ds_bpermute_b32 v23, v38, v22
	s_waitcnt lgkmcnt(0)
	v_add_f32_e32 v22, v22, v23
	ds_bpermute_b32 v23, v39, v22
	s_waitcnt lgkmcnt(0)
	v_add_f32_e32 v22, v22, v23
	ds_bpermute_b32 v23, v40, v22
	s_waitcnt lgkmcnt(0)
	v_add_f32_e32 v22, v22, v23
	ds_bpermute_b32 v23, v41, v22
	s_waitcnt lgkmcnt(0)
	v_add_f32_e32 v22, v22, v23
	ds_bpermute_b32 v23, v42, v22
	s_waitcnt lgkmcnt(0)
	v_add_f32_e32 v22, v22, v23
	v_fmamk_f32 v22, v22, 0x3c000000, v178
	v_cmp_gt_f32_e32 vcc, s2, v22
	v_mul_f32_e32 v23, 0x4b800000, v22
	s_nop 0
	v_cndmask_b32_e32 v22, v22, v23, vcc
	v_rsq_f32_e32 v22, v22
	s_nop 0
	v_mul_f32_e32 v23, 0x45800000, v22
	v_cndmask_b32_e32 v22, v22, v23, vcc
	v_pk_mul_f32 v[18:19], v[18:19], v[22:23] op_sel_hi:[1,0]
	v_pk_mul_f32 v[20:21], v[20:21], v[22:23] op_sel_hi:[1,0]
	v_pk_mul_f32 v[18:19], v[8:9], v[18:19]
	v_lshlrev_b32_e32 v22, 16, v16
	v_and_b32_e32 v16, 0xffff0000, v16
	v_mul_f32_e32 v18, v18, v22
	v_mul_f32_e32 v16, v19, v16
	v_pk_mul_f32 v[20:21], v[6:7], v[20:21]
	v_cvt_pk_bf16_f32 v16, v18, v16
	v_lshlrev_b32_e32 v18, 16, v17
	v_and_b32_e32 v17, 0xffff0000, v17
	v_mul_f32_e32 v18, v20, v18
	v_mul_f32_e32 v17, v21, v17
	v_cvt_pk_bf16_f32 v17, v18, v17
	v_add_co_u32_e32 v18, vcc, s92, v0
	s_nop 1
	v_addc_co_u32_e32 v19, vcc, 0, v1, vcc
	global_store_dwordx2 v[18:19], v[16:17], off
	ds_read_b128 v[16:19], v43 offset:11616
	s_waitcnt lgkmcnt(0)
	v_pk_mul_f32 v[20:21], v[18:19], v[18:19]
	v_pk_mul_f32 v[22:23], v[16:17], v[16:17]
	s_nop 0
	v_pk_mov_b32 v[24:25], v[22:23], v[20:21] op_sel:[1,0]
	v_mov_b32_e32 v23, v21
	v_pk_add_f32 v[20:21], v[24:25], v[22:23]
	s_nop 0
	v_add_f32_e32 v20, v20, v21
	ds_bpermute_b32 v21, v38, v20
	s_waitcnt lgkmcnt(0)
	v_add_f32_e32 v20, v20, v21
	ds_bpermute_b32 v21, v39, v20
	s_waitcnt lgkmcnt(0)
	v_add_f32_e32 v20, v20, v21
	ds_bpermute_b32 v21, v40, v20
	s_waitcnt lgkmcnt(0)
	v_add_f32_e32 v20, v20, v21
	ds_bpermute_b32 v21, v41, v20
	s_waitcnt lgkmcnt(0)
	v_add_f32_e32 v20, v20, v21
	ds_bpermute_b32 v21, v42, v20
	s_waitcnt lgkmcnt(0)
	v_add_f32_e32 v20, v20, v21
	v_fmamk_f32 v20, v20, 0x3c000000, v178
	v_cmp_gt_f32_e32 vcc, s2, v20
	v_mul_f32_e32 v21, 0x4b800000, v20
	s_nop 0
	v_cndmask_b32_e32 v20, v20, v21, vcc
	v_rsq_f32_e32 v20, v20
	s_nop 0
	v_mul_f32_e32 v21, 0x45800000, v20
	v_cndmask_b32_e32 v20, v20, v21, vcc
	v_pk_mul_f32 v[16:17], v[16:17], v[20:21] op_sel_hi:[1,0]
	v_pk_mul_f32 v[18:19], v[18:19], v[20:21] op_sel_hi:[1,0]
	v_pk_mul_f32 v[16:17], v[8:9], v[16:17]
	v_lshlrev_b32_e32 v20, 16, v14
	v_and_b32_e32 v14, 0xffff0000, v14
	v_mul_f32_e32 v16, v16, v20
	v_mul_f32_e32 v14, v17, v14
	v_pk_mul_f32 v[18:19], v[6:7], v[18:19]
	v_cvt_pk_bf16_f32 v14, v16, v14
	v_lshlrev_b32_e32 v16, 16, v15
	v_and_b32_e32 v15, 0xffff0000, v15
	v_mul_f32_e32 v16, v18, v16
	v_mul_f32_e32 v15, v19, v15
	v_cvt_pk_bf16_f32 v15, v16, v15
	v_add_co_u32_e32 v16, vcc, s3, v0
	s_nop 1
	v_addc_co_u32_e32 v17, vcc, 0, v1, vcc
	global_store_dwordx2 v[16:17], v[14:15], off
	ds_read_b128 v[14:17], v43 offset:12672
	s_waitcnt lgkmcnt(0)
; #define LAS __attribute__((address_space(3)))
; __device__ __forceinline__ float bf2f(unsigned h) { return __uint_as_float(h << 16); }
; __device__ __forceinline__ unsigned cvt_pk_bf16(float lo, float hi) { unsigned r; asm volatile("v_cvt_pk_bf16_f32 %0, %1, %2" : "=v"(r) : "v"(lo), "v"(hi)); return r; }
; template <bool SUBLN>
; __device__ __forceinline__ void attn_out(const AttnBufs& T, f32x16 (&o)[4], int type, int h, size_t orow0, LAS char* lds, int wid, int lane, int r32, int hi) {
;     ...
;     for (int i = 0; i < 16; ++i) {
;         f32x4 v = *(const LAS f32x4*)(stg + (2 * i + rr) * 132 + c4);
;         if (SUBLN) {
;             float s = (v[0] * v[0] + v[1] * v[1]) + (v[2] * v[2] + v[3] * v[3]);
;             s += __shfl_xor(s, 1); s += __shfl_xor(s, 2); s += __shfl_xor(s, 4); s += __shfl_xor(s, 8); s += __shfl_xor(s, 16);
;             v = v * (rsqrtf(s * (1.f / 128.f) + EPS)) * wsub;
;         }
;         u32x2 w; w.x = cvt_pk_bf16(v[0] * bf2f(gg[i].x & 0xffffu), v[1] * bf2f(gg[i].x >> 16)); w.y = cvt_pk_bf16(v[2] * bf2f(gg[i].y & 0xffffu), v[3] * bf2f(gg[i].y >> 16));
;         *(u32x2*)(op + (size_t)i * 2 * 3072) = w;
;     }
	v_pk_mul_f32 v[18:19], v[16:17], v[16:17]
	v_pk_mul_f32 v[20:21], v[14:15], v[14:15]
	s_nop 0
	v_pk_mov_b32 v[22:23], v[20:21], v[18:19] op_sel:[1,0]
	v_mov_b32_e32 v21, v19
	v_pk_add_f32 v[18:19], v[22:23], v[20:21]
	s_nop 0
	v_add_f32_e32 v18, v18, v19
	ds_bpermute_b32 v19, v38, v18
	s_waitcnt lgkmcnt(0)
	v_add_f32_e32 v18, v18, v19
	ds_bpermute_b32 v19, v39, v18
	s_waitcnt lgkmcnt(0)
	v_add_f32_e32 v18, v18, v19
	ds_bpermute_b32 v19, v40, v18
	s_waitcnt lgkmcnt(0)
	v_add_f32_e32 v18, v18, v19
	ds_bpermute_b32 v19, v41, v18
	s_waitcnt lgkmcnt(0)
	v_add_f32_e32 v18, v18, v19
	ds_bpermute_b32 v19, v42, v18
	s_waitcnt lgkmcnt(0)
	v_add_f32_e32 v18, v18, v19
	v_fmamk_f32 v18, v18, 0x3c000000, v178
	v_cmp_gt_f32_e32 vcc, s2, v18
	v_mul_f32_e32 v19, 0x4b800000, v18
	s_nop 0
	v_cndmask_b32_e32 v18, v18, v19, vcc
	v_rsq_f32_e32 v18, v18
	s_nop 0
	v_mul_f32_e32 v19, 0x45800000, v18
	v_cndmask_b32_e32 v18, v18, v19, vcc
	v_pk_mul_f32 v[14:15], v[14:15], v[18:19] op_sel_hi:[1,0]
	v_pk_mul_f32 v[16:17], v[16:17], v[18:19] op_sel_hi:[1,0]
	v_pk_mul_f32 v[14:15], v[8:9], v[14:15]
	v_lshlrev_b32_e32 v18, 16, v12
	v_and_b32_e32 v12, 0xffff0000, v12
	v_mul_f32_e32 v14, v14, v18
	v_mul_f32_e32 v12, v15, v12
	v_pk_mul_f32 v[16:17], v[6:7], v[16:17]
	v_cvt_pk_bf16_f32 v12, v14, v12
	v_lshlrev_b32_e32 v14, 16, v13
	v_and_b32_e32 v13, 0xffff0000, v13
	v_mul_f32_e32 v14, v16, v14
	v_mul_f32_e32 v13, v17, v13
	v_cvt_pk_bf16_f32 v13, v14, v13
	v_add_co_u32_e32 v14, vcc, s91, v0
	s_nop 1
	v_addc_co_u32_e32 v15, vcc, 0, v1, vcc
	global_store_dwordx2 v[14:15], v[12:13], off
	ds_read_b128 v[12:15], v43 offset:13728
	s_waitcnt lgkmcnt(0)
	v_pk_mul_f32 v[16:17], v[14:15], v[14:15]
	v_pk_mul_f32 v[18:19], v[12:13], v[12:13]
	s_nop 0
	v_pk_mov_b32 v[20:21], v[18:19], v[16:17] op_sel:[1,0]
	v_mov_b32_e32 v19, v17
	v_pk_add_f32 v[16:17], v[20:21], v[18:19]
	s_nop 0
	v_add_f32_e32 v16, v16, v17
	ds_bpermute_b32 v17, v38, v16
	s_waitcnt lgkmcnt(0)
	v_add_f32_e32 v16, v16, v17
	ds_bpermute_b32 v17, v39, v16
	s_waitcnt lgkmcnt(0)
	v_add_f32_e32 v16, v16, v17
	ds_bpermute_b32 v17, v40, v16
	s_waitcnt lgkmcnt(0)
	v_add_f32_e32 v16, v16, v17
	ds_bpermute_b32 v17, v41, v16
	s_waitcnt lgkmcnt(0)
	v_add_f32_e32 v16, v16, v17
	ds_bpermute_b32 v17, v42, v16
	s_waitcnt lgkmcnt(0)
	v_add_f32_e32 v16, v16, v17
	v_fmamk_f32 v16, v16, 0x3c000000, v178
	v_cmp_gt_f32_e32 vcc, s2, v16
	v_mul_f32_e32 v17, 0x4b800000, v16
	s_nop 0
	v_cndmask_b32_e32 v16, v16, v17, vcc
	v_rsq_f32_e32 v16, v16
	s_nop 0
	v_mul_f32_e32 v17, 0x45800000, v16
	v_cndmask_b32_e32 v16, v16, v17, vcc
	v_pk_mul_f32 v[12:13], v[12:13], v[16:17] op_sel_hi:[1,0]
	v_pk_mul_f32 v[14:15], v[14:15], v[16:17] op_sel_hi:[1,0]
	v_pk_mul_f32 v[12:13], v[8:9], v[12:13]
	v_lshlrev_b32_e32 v16, 16, v10
	v_and_b32_e32 v10, 0xffff0000, v10
	v_mul_f32_e32 v12, v12, v16
	v_mul_f32_e32 v10, v13, v10
	v_pk_mul_f32 v[14:15], v[6:7], v[14:15]
	v_cvt_pk_bf16_f32 v10, v12, v10
	v_lshlrev_b32_e32 v12, 16, v11
	v_and_b32_e32 v11, 0xffff0000, v11
	v_mul_f32_e32 v12, v14, v12
	v_mul_f32_e32 v11, v15, v11
	v_cvt_pk_bf16_f32 v11, v12, v11
	v_add_co_u32_e32 v12, vcc, s33, v0
	s_nop 1
	v_addc_co_u32_e32 v13, vcc, 0, v1, vcc
	global_store_dwordx2 v[12:13], v[10:11], off
	ds_read_b128 v[10:13], v43 offset:14784
	s_waitcnt lgkmcnt(0)
	v_pk_mul_f32 v[14:15], v[12:13], v[12:13]
	v_pk_mul_f32 v[16:17], v[10:11], v[10:11]
	s_nop 0
	v_pk_mov_b32 v[18:19], v[16:17], v[14:15] op_sel:[1,0]
	v_mov_b32_e32 v17, v15
	v_pk_add_f32 v[14:15], v[18:19], v[16:17]
	s_nop 0
	v_add_f32_e32 v14, v14, v15
	ds_bpermute_b32 v15, v38, v14
	s_waitcnt lgkmcnt(0)
	v_add_f32_e32 v14, v14, v15
	ds_bpermute_b32 v15, v39, v14
	s_waitcnt lgkmcnt(0)
	v_add_f32_e32 v14, v14, v15
	ds_bpermute_b32 v15, v40, v14
	s_waitcnt lgkmcnt(0)
	v_add_f32_e32 v14, v14, v15
	ds_bpermute_b32 v15, v41, v14
	s_waitcnt lgkmcnt(0)
	v_add_f32_e32 v14, v14, v15
	ds_bpermute_b32 v15, v42, v14
	s_waitcnt lgkmcnt(0)
	v_add_f32_e32 v14, v14, v15
	v_fmamk_f32 v14, v14, 0x3c000000, v178
	v_cmp_gt_f32_e32 vcc, s2, v14
	v_mul_f32_e32 v15, 0x4b800000, v14
	s_nop 0
	v_cndmask_b32_e32 v14, v14, v15, vcc
	v_rsq_f32_e32 v14, v14
	s_nop 0
	v_mul_f32_e32 v15, 0x45800000, v14
	v_cndmask_b32_e32 v14, v14, v15, vcc
	v_pk_mul_f32 v[10:11], v[10:11], v[14:15] op_sel_hi:[1,0]
	v_pk_mul_f32 v[12:13], v[12:13], v[14:15] op_sel_hi:[1,0]
	v_pk_mul_f32 v[10:11], v[8:9], v[10:11]
	v_lshlrev_b32_e32 v14, 16, v4
	v_and_b32_e32 v4, 0xffff0000, v4
	v_mul_f32_e32 v10, v10, v14
	v_mul_f32_e32 v4, v11, v4
	v_pk_mul_f32 v[12:13], v[6:7], v[12:13]
	v_cvt_pk_bf16_f32 v4, v10, v4
	v_lshlrev_b32_e32 v10, 16, v5
	v_and_b32_e32 v5, 0xffff0000, v5
	v_mul_f32_e32 v10, v12, v10
	v_mul_f32_e32 v5, v13, v5
	v_cvt_pk_bf16_f32 v5, v10, v5
	v_add_co_u32_e32 v10, vcc, s94, v0
	s_nop 1
	v_addc_co_u32_e32 v11, vcc, 0, v1, vcc
	global_store_dwordx2 v[10:11], v[4:5], off
	ds_read_b128 v[10:13], v43 offset:15840
	s_waitcnt lgkmcnt(0)
	v_pk_mul_f32 v[4:5], v[12:13], v[12:13]
	v_pk_mul_f32 v[14:15], v[10:11], v[10:11]
	s_nop 0
	v_pk_mov_b32 v[16:17], v[14:15], v[4:5] op_sel:[1,0]
	v_mov_b32_e32 v15, v5
	v_pk_add_f32 v[4:5], v[16:17], v[14:15]
	s_nop 0
	v_add_f32_e32 v4, v4, v5
	ds_bpermute_b32 v5, v38, v4
	s_waitcnt lgkmcnt(0)
	v_add_f32_e32 v4, v4, v5
	ds_bpermute_b32 v5, v39, v4
	s_waitcnt lgkmcnt(0)
	v_add_f32_e32 v4, v4, v5
	ds_bpermute_b32 v5, v40, v4
	s_waitcnt lgkmcnt(0)
	v_add_f32_e32 v4, v4, v5
	ds_bpermute_b32 v5, v41, v4
	s_waitcnt lgkmcnt(0)
	v_add_f32_e32 v4, v4, v5
	ds_bpermute_b32 v5, v42, v4
	s_waitcnt lgkmcnt(0)
	v_add_f32_e32 v4, v4, v5
	v_fmamk_f32 v4, v4, 0x3c000000, v178
	v_cmp_gt_f32_e32 vcc, s2, v4
	v_mul_f32_e32 v5, 0x4b800000, v4
	s_nop 0
	v_cndmask_b32_e32 v4, v4, v5, vcc
	v_rsq_f32_e32 v4, v4
	s_nop 0
	v_mul_f32_e32 v5, 0x45800000, v4
	v_cndmask_b32_e32 v4, v4, v5, vcc
	v_pk_mul_f32 v[10:11], v[10:11], v[4:5] op_sel_hi:[1,0]
	v_pk_mul_f32 v[4:5], v[12:13], v[4:5] op_sel_hi:[1,0]
	s_nop 0
	v_pk_mul_f32 v[4:5], v[6:7], v[4:5]
	v_pk_mul_f32 v[6:7], v[8:9], v[10:11]
	v_lshlrev_b32_e32 v8, 16, v2
	v_and_b32_e32 v2, 0xffff0000, v2
	v_mul_f32_e32 v6, v6, v8
	v_mul_f32_e32 v2, v7, v2
	v_cvt_pk_bf16_f32 v2, v6, v2
	v_lshlrev_b32_e32 v6, 16, v3
	v_and_b32_e32 v3, 0xffff0000, v3
	v_mul_f32_e32 v3, v5, v3
	v_mul_f32_e32 v4, v4, v6
	v_cvt_pk_bf16_f32 v3, v4, v3

; #define LAS __attribute__((address_space(3)))
; #define SBAR() __builtin_amdgcn_sched_barrier(0)
; #define VMW0() asm volatile("s_waitcnt vmcnt(0)" ::: "memory")
; template <int DQK>
; __device__ __forceinline__ void qkt(f32x16& p0, f32x16& p1, const LAS char* Ks, const bf16x8 (&qr)[DQK / 16], const int (&ka)[8], float nMB) {
;     ...
;     for (int d0 = 0; d0 < DQK / 16; ++d0) {
;         const LAS char* a = Ks + ka[d0 % NA] + (d0 / NA) * (NA * 32);
;         const bf16x8 b0 = *(const LAS bf16x8*)(a);
;         const bf16x8 b1 = *(const LAS bf16x8*)(a + 32 * RB);
;         p0 = __builtin_amdgcn_mfma_f32_32x32x16_bf16(b0, qr[d0], p0, 0, 0, 0);
;         p1 = __builtin_amdgcn_mfma_f32_32x32x16_bf16(b1, qr[d0], p1, 0, 0, 0); }
; template <int DQK, bool DOUBLE> ...
;     ...
;         for (int j = 0; j < NT; ++j) {
;             SBAR(); qkt<DQK>(p0, p1, K_lds + bc * K_STRIDE, qr, ka, nMB);
;             partialSM(p0, p1); finishSM(p0, p1, l_reg, pa0, pa1, pa2, pa3); SBAR();
;             pv_d0(o, vb0 + bc * V_BYTES, pa0, pa1, pa2, pa3);
;             if (j + 1 < NT) { VMW0(); __syncthreads(); if (j + 3 < NT) DMA(j + 3, bc); }
.LBB0_173:
	s_mov_b32 s31, s4
	s_mov_b32 s4, s33
	s_mul_i32 s33, s5, 0x6000
	s_add_i32 s33, s33, 0
	s_lshl_b32 s35, s5, 14
	s_lshl_b32 s100, s4, 14
	s_add_i32 s100, s100, s3
	s_mul_i32 s101, s4, 0x6000
	s_add_i32 s101, s101, s2
	s_add_i32 s41, s21, 3
	s_cmp_lt_i32 s41, s71
	s_cselect_b64 vcc, -1, 0
	s_cmp_lg_u32 s21, 0
	s_cselect_b64 vcc, vcc, 0
	v_add_u32_e32 v184, s35, v170
	s_waitcnt lgkmcnt(2)
	v_mfma_f32_32x32x16_bf16 v[96:111], v[204:207], v[112:115], v[0:15]
	ds_read_b128 v[216:219], v193 offset:49152
	s_waitcnt lgkmcnt(2)
	v_mfma_f32_32x32x16_bf16 v[96:111], v[208:211], v[116:119], v[96:111]
	ds_read_b128 v[204:207], v194 offset:49152
	s_cbranch_vccz .Lattn_dma_A_1
	s_ashr_i32 s45, s44, 31
	v_lshl_add_u64 v[172:173], s[44:45], 0, v[146:147]
	v_lshlrev_b64 v[172:173], 9, v[172:173]
	v_lshl_add_u64 v[172:173], v[154:155], 0, v[172:173]
	s_mov_b32 m0, s100
	s_nop 0
	global_load_lds_dwordx4 v[172:173], off
.Lattn_dma_A_1:
	s_waitcnt lgkmcnt(2)
	v_mfma_f32_32x32x16_bf16 v[96:111], v[212:215], v[120:123], v[96:111]
	ds_read_b128 v[208:211], v195 offset:49152
	s_cbranch_vccz .Lattn_dma_A_2
	v_lshl_add_u64 v[172:173], s[44:45], 0, v[148:149]
	v_lshlrev_b64 v[172:173], 9, v[172:173]
	v_lshl_add_u64 v[172:173], v[154:155], 0, v[172:173]
	s_add_i32 m0, s100, 0x2000
	s_nop 0
	global_load_lds_dwordx4 v[172:173], off
.Lattn_dma_A_2:
	s_waitcnt lgkmcnt(2)
	v_mfma_f32_32x32x16_bf16 v[96:111], v[216:219], v[124:127], v[96:111]
	ds_read_b128 v[212:215], v196 offset:49152
	s_cbranch_vccz .Lattn_dma_A_3
	v_lshl_add_u64 v[172:173], s[44:45], 0, v[150:151]
	v_lshlrev_b64 v[172:173], 9, v[172:173]
	s_add_i32 m0, s101, 0xc000
	v_lshl_add_u64 v[172:173], v[156:157], 0, v[172:173]
	global_load_lds_dwordx4 v[172:173], off
.Lattn_dma_A_3:
	s_waitcnt lgkmcnt(2)
	v_mfma_f32_32x32x16_bf16 v[96:111], v[204:207], v[128:131], v[96:111]
	ds_read_b128 v[216:219], v197 offset:49152
	s_cbranch_vccz .Lattn_dma_A_4
	v_lshl_add_u64 v[172:173], s[44:45], 0, v[152:153]
	v_lshlrev_b64 v[172:173], 9, v[172:173]
	v_lshl_add_u64 v[172:173], v[158:159], 0, v[172:173]
	s_add_i32 m0, s101, 0xe000
	s_nop 0
	global_load_lds_dwordx4 v[172:173], off
	s_add_i32 s44, s44, 64
.Lattn_dma_A_4:
	s_waitcnt lgkmcnt(2)
	v_mfma_f32_32x32x16_bf16 v[96:111], v[208:211], v[132:135], v[96:111]
	ds_read_b128 v[204:207], v174 offset:57344
	s_waitcnt lgkmcnt(2)
	v_mfma_f32_32x32x16_bf16 v[96:111], v[212:215], v[136:139], v[96:111]
	ds_read_b128 v[208:211], v175 offset:57344
	s_waitcnt lgkmcnt(2)
	v_mfma_f32_32x32x16_bf16 v[96:111], v[216:219], v[140:143], v[96:111]
	ds_read_b128 v[212:215], v192 offset:57344
	s_waitcnt lgkmcnt(2)
	v_mfma_f32_32x32x16_bf16 v[80:95], v[204:207], v[112:115], v[0:15]
	ds_read_b128 v[216:219], v193 offset:57344
	s_waitcnt lgkmcnt(2)
	v_mfma_f32_32x32x16_bf16 v[80:95], v[208:211], v[116:119], v[80:95]
	ds_read_b128 v[204:207], v194 offset:57344
	s_nop 4
	v_exp_f32_e32 v96, v96
	v_exp_f32_e32 v97, v97
	v_exp_f32_e32 v104, v104
	v_exp_f32_e32 v105, v105
	s_waitcnt lgkmcnt(2)
	v_mfma_f32_32x32x16_bf16 v[80:95], v[212:215], v[120:123], v[80:95]
	ds_read_b128 v[208:211], v195 offset:57344
	v_exp_f32_e32 v98, v98
	v_exp_f32_e32 v99, v99
	v_exp_f32_e32 v106, v106
	s_waitcnt lgkmcnt(2)
	v_mfma_f32_32x32x16_bf16 v[80:95], v[216:219], v[124:127], v[80:95]
	ds_read_b128 v[212:215], v196 offset:57344
	v_exp_f32_e32 v100, v100
	v_exp_f32_e32 v101, v101
	v_exp_f32_e32 v107, v107
	s_waitcnt lgkmcnt(2)
	v_mfma_f32_32x32x16_bf16 v[80:95], v[204:207], v[128:131], v[80:95]
	ds_read_b128 v[216:219], v197 offset:57344
	v_exp_f32_e32 v102, v102
	v_exp_f32_e32 v103, v103
	v_exp_f32_e32 v108, v108
	s_waitcnt lgkmcnt(2)
	v_mfma_f32_32x32x16_bf16 v[80:95], v[208:211], v[132:135], v[80:95]
	ds_read_b64_tr_b16 v[204:205], v184 offset:0
	ds_read_b64_tr_b16 v[206:207], v184 offset:2048
	v_cvt_pk_bf16_f32 v172, v96, v97
	v_cvt_pk_bf16_f32 v173, v98, v99
	v_exp_f32_e32 v109, v109
	s_waitcnt lgkmcnt(3)
	v_mfma_f32_32x32x16_bf16 v[80:95], v[212:215], v[136:139], v[80:95]
	ds_read_b64_tr_b16 v[208:209], v184 offset:512
	ds_read_b64_tr_b16 v[210:211], v184 offset:2560
	v_cvt_pk_bf16_f32 v174, v100, v101
	v_exp_f32_e32 v110, v110
	s_waitcnt lgkmcnt(4)
	v_mfma_f32_32x32x16_bf16 v[80:95], v[216:219], v[140:143], v[80:95]
	ds_read_b64_tr_b16 v[212:213], v184 offset:1024
	ds_read_b64_tr_b16 v[214:215], v184 offset:3072
	v_cvt_pk_bf16_f32 v175, v102, v103
	v_exp_f32_e32 v111, v111
	v_add_f32_e32 v96, 0, v96
	v_add_f32_e32 v96, v97, v96
	s_waitcnt lgkmcnt(4)
	v_mfma_f32_32x32x16_bf16 v[16:31], v[172:175], v[204:207], v[16:31]
	ds_read_b64_tr_b16 v[216:217], v184 offset:1536
	ds_read_b64_tr_b16 v[218:219], v184 offset:3584
	v_cvt_pk_bf16_f32 v192, v104, v105
	v_add_f32_e32 v96, v98, v96
	v_add_f32_e32 v96, v99, v96
	v_add_f32_e32 v96, v100, v96
	s_waitcnt lgkmcnt(4)
; #define SBAR() __builtin_amdgcn_sched_barrier(0)
; #define PK8(P, BASE, OUT) do { u32x4 w = {cvt_pk_bf16(P[BASE + 0], P[BASE + 1]), cvt_pk_bf16(P[BASE + 2], P[BASE + 3]), cvt_pk_bf16(P[BASE + 4], P[BASE + 5]), cvt_pk_bf16(P[BASE + 6], P[BASE + 7])}; \
;     OUT = *reinterpret_cast<bf16x8*>(&w); } while (0)
; #define VMW0() asm volatile("s_waitcnt vmcnt(0)" ::: "memory")
; template <int D0> __device__ __forceinline__ void pv_one(f32x16& od, unsigned vb, bf16x8 pa0, bf16x8 pa1, bf16x8 pa2, bf16x8 pa3) {
;     const s16x4 l0 = tr_read<v_rd_off(D0, 0, 0)>(vb), h0 = tr_read<v_rd_off(D0, 0, 1)>(vb), l1 = tr_read<v_rd_off(D0, 1, 0)>(vb), h1 = tr_read<v_rd_off(D0, 1, 1)>(vb);
;     const s16x4 l2 = tr_read<v_rd_off(D0, 2, 0)>(vb), h2 = tr_read<v_rd_off(D0, 2, 1)>(vb), l3 = tr_read<v_rd_off(D0, 3, 0)>(vb), h3 = tr_read<v_rd_off(D0, 3, 1)>(vb);
;     asm volatile("s_waitcnt lgkmcnt(0)" ::: "memory"); SBAR();
;     ...
;     od = __builtin_amdgcn_mfma_f32_32x32x16_bf16(pa0, PK(l0, h0), od, 0, 0, 0);
;     od = __builtin_amdgcn_mfma_f32_32x32x16_bf16(pa1, PK(l1, h1), od, 0, 0, 0);
;     od = __builtin_amdgcn_mfma_f32_32x32x16_bf16(pa2, PK(l2, h2), od, 0, 0, 0);
;     od = __builtin_amdgcn_mfma_f32_32x32x16_bf16(pa3, PK(l3, h3), od, 0, 0, 0);
;     ...
; }
; __device__ __forceinline__ void pv_d0(f32x16 (&o)[4], unsigned vb, bf16x8 pa0, bf16x8 pa1, bf16x8 pa2, bf16x8 pa3) {
;     pv_one<0>(o[0], vb, pa0, pa1, pa2, pa3); pv_one<1>(o[1], vb, pa0, pa1, pa2, pa3); pv_one<2>(o[2], vb, pa0, pa1, pa2, pa3); pv_one<3>(o[3], vb, pa0, pa1, pa2, pa3);
; }
; __device__ __forceinline__ void partialSM(f32x16& p0, f32x16& p1) {
; #pragma unroll
;     for (int r = 0; r < 16; ++r) p0[r] = __builtin_amdgcn_exp2f(p0[r]);
; }
; __device__ __forceinline__ void finishSM(f32x16& p0, f32x16& p1, float& l_reg, bf16x8& pa0, bf16x8& pa1, bf16x8& pa2, bf16x8& pa3) {
; #pragma unroll
;     for (int r = 0; r < 16; ++r) p1[r] = __builtin_amdgcn_exp2f(p1[r]);
;     float ps = 0;
; #pragma unroll
;     for (int r = 0; r < 16; ++r) ps += p0[r];
; #pragma unroll
;     for (int r = 0; r < 16; ++r) ps += p1[r];
;     l_reg += ps;
;     ...
;     PK8(p0, 0, pa0); PK8(p0, 8, pa1); PK8(p1, 0, pa2); PK8(p1, 8, pa3);
; template <int DQK, bool DOUBLE> ...
;     ...
;             if (j + 1 < NT) { VMW0(); __syncthreads(); if (j + 3 < NT) DMA(j + 3, bc); }
;             { const int _t = bc; bc = bn; bn = bf; bf = _t; }
	v_mfma_f32_32x32x16_bf16 v[32:47], v[172:175], v[208:211], v[32:47]
	ds_read_b64_tr_b16 v[204:205], v184 offset:4096
	ds_read_b64_tr_b16 v[206:207], v184 offset:6144
	v_cvt_pk_bf16_f32 v193, v106, v107
	v_exp_f32_e32 v80, v80
	v_exp_f32_e32 v81, v81
	v_exp_f32_e32 v88, v88
	v_exp_f32_e32 v89, v89
	v_add_f32_e32 v96, v101, v96
	v_add_f32_e32 v96, v102, v96
	s_waitcnt lgkmcnt(4)
	v_mfma_f32_32x32x16_bf16 v[48:63], v[172:175], v[212:215], v[48:63]
	ds_read_b64_tr_b16 v[208:209], v184 offset:4608
	ds_read_b64_tr_b16 v[210:211], v184 offset:6656
	v_cvt_pk_bf16_f32 v194, v108, v109
	v_exp_f32_e32 v82, v82
	v_exp_f32_e32 v83, v83
	v_exp_f32_e32 v90, v90
	v_add_f32_e32 v96, v103, v96
	s_waitcnt lgkmcnt(4)
	v_mfma_f32_32x32x16_bf16 v[64:79], v[172:175], v[216:219], v[64:79]
	ds_read_b64_tr_b16 v[212:213], v184 offset:5120
	ds_read_b64_tr_b16 v[214:215], v184 offset:7168
	v_cvt_pk_bf16_f32 v195, v110, v111
	v_exp_f32_e32 v84, v84
	v_exp_f32_e32 v85, v85
	v_exp_f32_e32 v91, v91
	v_add_f32_e32 v96, v104, v96
	v_add_f32_e32 v96, v105, v96
	s_waitcnt lgkmcnt(4)
	v_mfma_f32_32x32x16_bf16 v[16:31], v[192:195], v[204:207], v[16:31]
	ds_read_b64_tr_b16 v[216:217], v184 offset:5632
	ds_read_b64_tr_b16 v[218:219], v184 offset:7680
	v_exp_f32_e32 v86, v86
	v_exp_f32_e32 v87, v87
	v_exp_f32_e32 v92, v92
	v_add_f32_e32 v96, v106, v96
	v_add_f32_e32 v96, v107, v96
	s_waitcnt lgkmcnt(4)
	v_mfma_f32_32x32x16_bf16 v[32:47], v[192:195], v[208:211], v[32:47]
	ds_read_b64_tr_b16 v[204:205], v184 offset:8192
	ds_read_b64_tr_b16 v[206:207], v184 offset:10240
	v_cvt_pk_bf16_f32 v196, v80, v81
	v_cvt_pk_bf16_f32 v197, v82, v83
	v_exp_f32_e32 v93, v93
	v_add_f32_e32 v96, v108, v96
	v_add_f32_e32 v96, v109, v96
	s_waitcnt lgkmcnt(4)
	v_mfma_f32_32x32x16_bf16 v[48:63], v[192:195], v[212:215], v[48:63]
	ds_read_b64_tr_b16 v[208:209], v184 offset:8704
	ds_read_b64_tr_b16 v[210:211], v184 offset:10752
	v_cvt_pk_bf16_f32 v198, v84, v85
	v_exp_f32_e32 v94, v94
	v_add_f32_e32 v96, v110, v96
	v_add_f32_e32 v96, v111, v96
	s_waitcnt lgkmcnt(4)
	v_mfma_f32_32x32x16_bf16 v[64:79], v[192:195], v[216:219], v[64:79]
	ds_read_b64_tr_b16 v[212:213], v184 offset:9216
	ds_read_b64_tr_b16 v[214:215], v184 offset:11264
	v_cvt_pk_bf16_f32 v199, v86, v87
	v_exp_f32_e32 v95, v95
	v_add_f32_e32 v80, v80, v96
	v_add_f32_e32 v80, v81, v80
	s_waitcnt lgkmcnt(4)
	v_mfma_f32_32x32x16_bf16 v[16:31], v[196:199], v[204:207], v[16:31]
	ds_read_b64_tr_b16 v[216:217], v184 offset:9728
	ds_read_b64_tr_b16 v[218:219], v184 offset:11776
	v_cvt_pk_bf16_f32 v200, v88, v89
	v_add_f32_e32 v80, v82, v80
	v_add_f32_e32 v80, v83, v80
	v_add_f32_e32 v80, v84, v80
	s_waitcnt lgkmcnt(4)
	v_mfma_f32_32x32x16_bf16 v[32:47], v[196:199], v[208:211], v[32:47]
	ds_read_b64_tr_b16 v[204:205], v184 offset:12288
	ds_read_b64_tr_b16 v[206:207], v184 offset:14336
	v_cvt_pk_bf16_f32 v201, v90, v91
	v_add_f32_e32 v80, v85, v80
	v_add_f32_e32 v80, v86, v80
	v_add_f32_e32 v80, v87, v80
	s_waitcnt lgkmcnt(4)
	v_mfma_f32_32x32x16_bf16 v[48:63], v[196:199], v[212:215], v[48:63]
	ds_read_b64_tr_b16 v[208:209], v184 offset:12800
	ds_read_b64_tr_b16 v[210:211], v184 offset:14848
	v_cvt_pk_bf16_f32 v202, v92, v93
	s_waitcnt lgkmcnt(4)
	v_mfma_f32_32x32x16_bf16 v[64:79], v[196:199], v[216:219], v[64:79]
	ds_read_b64_tr_b16 v[212:213], v184 offset:13312
	ds_read_b64_tr_b16 v[214:215], v184 offset:15360
	v_cvt_pk_bf16_f32 v203, v94, v95
	v_add_f32_e32 v80, v88, v80
	v_add_f32_e32 v80, v89, v80
	v_add_f32_e32 v80, v90, v80
	s_waitcnt lgkmcnt(4)
	v_mfma_f32_32x32x16_bf16 v[16:31], v[200:203], v[204:207], v[16:31]
	ds_read_b64_tr_b16 v[216:217], v184 offset:13824
	ds_read_b64_tr_b16 v[218:219], v184 offset:15872
	s_mul_i32 s41, s31, 0x6000
	v_add_u32_e32 v174, s41, v145
	v_add_u32_e32 v175, s41, v161
	v_add_u32_e32 v192, s41, v164
	v_add_u32_e32 v193, s41, v165
	v_add_u32_e32 v194, s41, v166
	v_add_u32_e32 v195, s41, v167
	v_add_u32_e32 v196, s41, v168
	v_add_u32_e32 v197, s41, v169
	v_add_f32_e32 v80, v91, v80
	v_add_f32_e32 v80, v92, v80
	v_add_f32_e32 v80, v93, v80
	v_add_f32_e32 v80, v94, v80
	s_waitcnt lgkmcnt(4)
	v_mfma_f32_32x32x16_bf16 v[32:47], v[200:203], v[208:211], v[32:47]
	ds_read_b128 v[204:207], v174 offset:49152
	v_add_f32_e32 v80, v95, v80
	s_waitcnt lgkmcnt(3)
	v_mfma_f32_32x32x16_bf16 v[48:63], v[200:203], v[212:215], v[48:63]
	ds_read_b128 v[208:211], v175 offset:49152
	s_waitcnt lgkmcnt(2)
	v_mfma_f32_32x32x16_bf16 v[64:79], v[200:203], v[216:219], v[64:79]
	ds_read_b128 v[212:215], v192 offset:49152
	s_add_i32 s41, s21, 2
	s_cmp_ge_i32 s41, s71
	s_cbranch_scc1 .LBB0_176
	s_waitcnt vmcnt(0)
	s_barrier
.LBB0_176:
	s_add_i32 s21, s21, 1
	s_cmp_lg_u32 s20, s21
	v_add_f32_e32 v171, v171, v80
	s_cbranch_scc0 .LBB0_178
	s_mov_b32 s33, s5
	s_mov_b32 s5, s31
	s_branch .LBB0_173

; __global__ void __launch_bounds__(512, 2) mega_fwd(Args args) {
	.amdhsa_kernel _Z8mega_fwd4Args
		.amdhsa_group_segment_fixed_size 0
		.amdhsa_private_segment_fixed_size 0
		.amdhsa_kernarg_size 520
		.amdhsa_user_sgpr_count 2
		.amdhsa_user_sgpr_dispatch_ptr 0
		.amdhsa_user_sgpr_queue_ptr 0
		.amdhsa_user_sgpr_kernarg_segment_ptr 1
		.amdhsa_user_sgpr_dispatch_id 0
		.amdhsa_user_sgpr_kernarg_preload_length 0
		.amdhsa_user_sgpr_kernarg_preload_offset 0
		.amdhsa_user_sgpr_private_segment_size 0
		.amdhsa_uses_dynamic_stack 0
		.amdhsa_enable_private_segment 0
		.amdhsa_system_sgpr_workgroup_id_x 1
		.amdhsa_system_sgpr_workgroup_id_y 0
		.amdhsa_system_sgpr_workgroup_id_z 0
		.amdhsa_system_sgpr_workgroup_info 0
		.amdhsa_system_vgpr_workitem_id 2
		.amdhsa_next_free_vgpr 256
		.amdhsa_next_free_sgpr 102
		.amdhsa_accum_offset 256
		.amdhsa_reserve_vcc 1
		.amdhsa_float_round_mode_32 0
		.amdhsa_float_round_mode_16_64 0
		.amdhsa_float_denorm_mode_32 3
		.amdhsa_float_denorm_mode_16_64 3
		.amdhsa_dx10_clamp 1
		.amdhsa_ieee_mode 1
		.amdhsa_fp16_overflow 0
		.amdhsa_tg_split 0
		.amdhsa_exception_fp_ieee_invalid_op 0
		.amdhsa_exception_fp_denorm_src 0
		.amdhsa_exception_fp_ieee_div_zero 0
		.amdhsa_exception_fp_ieee_overflow 0
		.amdhsa_exception_fp_ieee_underflow 0
		.amdhsa_exception_fp_ieee_inexact 0
		.amdhsa_exception_int_div_zero 0
	.end_amdhsa_kernel

; __global__ void __launch_bounds__(512, 2) mega_fwd(Args args) {
amdhsa.kernels:
  - .agpr_count:     0
    .args:
      - .offset:         0
        .size:           264
        .value_kind:     by_value
      - .offset:         264
        .size:           4
        .value_kind:     hidden_block_count_x
      - .offset:         268
        .size:           4
        .value_kind:     hidden_block_count_y
      - .offset:         272
        .size:           4
        .value_kind:     hidden_block_count_z
      - .offset:         276
        .size:           2
        .value_kind:     hidden_group_size_x
      - .offset:         278
        .size:           2
        .value_kind:     hidden_group_size_y
      - .offset:         280
        .size:           2
        .value_kind:     hidden_group_size_z
      - .offset:         282
        .size:           2
        .value_kind:     hidden_remainder_x
      - .offset:         284
        .size:           2
        .value_kind:     hidden_remainder_y
      - .offset:         286
        .size:           2
        .value_kind:     hidden_remainder_z
      - .offset:         304
        .size:           8
        .value_kind:     hidden_global_offset_x
      - .offset:         312
        .size:           8
        .value_kind:     hidden_global_offset_y
      - .offset:         320
        .size:           8
        .value_kind:     hidden_global_offset_z
      - .offset:         328
        .size:           2
        .value_kind:     hidden_grid_dims
      - .offset:         352
        .size:           8
        .value_kind:     hidden_multigrid_sync_arg
      - .offset:         384
        .size:           4
        .value_kind:     hidden_dynamic_lds_size
    .group_segment_fixed_size: 0
    .kernarg_segment_align: 8
    .kernarg_segment_size: 520
    .language:       OpenCL C
    .language_version:
      - 2
      - 0
    .max_flat_workgroup_size: 512
    .name:           _Z8mega_fwd4Args
    .private_segment_fixed_size: 0
    .sgpr_count:     108
    .sgpr_spill_count: 304
    .symbol:         _Z8mega_fwd4Args.kd
    .uniform_work_group_size: 1
    .uses_dynamic_stack: false
    .vgpr_count:     256
    .vgpr_spill_count: 0
    .wavefront_size: 64
